# pair loop: next tile's first k-slab is requested before the current tile's stores (cross-tile prefetch)
# baseline (speedup 1.0000x reference)
; DI int opaque_tid() { int t = threadIdx.x; asm volatile("" : "+v"(t)); return t; }
; template <bool SWAP, class Epi>
; DI void gemm_tile(const u16* __restrict__ A, int lda, const u16* __restrict__ Bw, int ldb, int K, char* lds, Epi epi) {
;   const int tid = opaque_tid(), lane = tid & 63, w = tid >> 6, r = lane & 31, h = lane >> 5;
;   const int wm = w & 3, wn = w >> 2;
;   f32x16 acc[2][2];
; #pragma unroll
;   for (int a = 0; a < 2; ++a)
; #pragma unroll
;     for (int b = 0; b < 2; ++b)
; #pragma unroll
;       for (int i = 0; i < 16; ++i) acc[a][b][i] = 0.f;
;   const int lrow = tid >> 3, lkc = tid & 7;
;   u32x4 ra0[4], rb0[2], ra1[4], rb1[2];
;   const u16* ap = A + (size_t)lrow * lda + lkc * 8;
;   const u16* bp = Bw + (size_t)lrow * ldb + lkc * 8;
;   const int nk = K >> 6;
;   auto gload = [&](int kt, u32x4* ra, u32x4* rb) {
; #pragma unroll
;     for (int j = 0; j < 4; ++j) ra[j] = *(const u32x4*)(ap + (size_t)(64 * j) * lda + kt * 64);
; #pragma unroll
;     for (int j = 0; j < 2; ++j) rb[j] = *(const u32x4*)(bp + (size_t)(64 * j) * ldb + kt * 64);
;   };
;   auto lstore = [&](int st, const u32x4* ra, const u32x4* rb) {
;     char* base = lds + st * GEMM_STAGE;
; #pragma unroll
;     for (int j = 0; j < 4; ++j) *(u32x4*)(base + ((lrow + 64 * j) * 72 + lkc * 8) * 2) = ra[j];
; #pragma unroll
;     for (int j = 0; j < 2; ++j) *(u32x4*)(base + 36864 + ((lrow + 64 * j) * 72 + lkc * 8) * 2) = rb[j];
; DI void inproj_tile(const Params& p, int l, int mt, int nt, char* lds) {
;   const int tid = opaque_tid(), lane = tid & 63, w = tid >> 6, r = lane & 31, h = lane >> 5;
;   const int wm = w & 3, wn = w >> 2;
;   const int m0 = mt * 256;
;   const u16* A = p.Xb + (size_t)m0 * DM;
;   const u16* Bw = p.Wt_in + (size_t)(l & 1) * NIN * DM + (size_t)nt * 128 * DM;
.LBB0_320:
	v_readlane_b32 s0, v240, 17
	v_readlane_b32 s1, v240, 18
	s_andn2_b64 vcc, exec, s[0:1]
	s_lshl_b32 s0, s38, 4
	s_lshl_b32 s50, s38, 3
	v_writelane_b32 v238, s0, 45
	s_nop 1
	v_writelane_b32 v238, s1, 46
	s_cbranch_vccnz .LBB0_370
	s_bitcmp1_b32 s38, 0
	v_readlane_b32 s4, v241, 16
	s_cselect_b32 s0, 0xc00000, 0
	s_add_u32 s18, s4, s0
	v_readlane_b32 s0, v238, 45
	v_readlane_b32 s5, v241, 17
	s_addc_u32 s19, s5, 0
	s_mov_b32 s1, s61
	s_mov_b32 s2, s0
	v_writelane_b32 v238, s2, 45
	s_lshl_b64 s[0:1], s[0:1], 2
	v_readlane_b32 s6, v241, 42
	v_writelane_b32 v238, s3, 46
	v_readlane_b32 s7, v241, 43
	v_readlane_b32 s10, v241, 46
	s_add_u32 s20, s6, s0
	s_addc_u32 s21, s7, s1
	s_lshl_b32 s22, s10, 7
	v_readlane_b32 s23, v238, 17
	v_readlane_b32 s0, v238, 16
	s_and_b32 s41, s0, 7
	s_lshr_b32 s101, s0, 3
	s_cmp_gt_u32 s41, 5
	s_cbranch_scc1 .Lpp_done
	v_readlane_b32 s8, v241, 24
	v_readlane_b32 s9, v241, 25
	v_lshrrev_b32_e32 v0, 6, v152
	v_and_b32_e32 v1, 63, v152
	s_nop 0
	v_readfirstlane_b32 s3, v0
	s_lshl_b32 s13, s3, 16
	s_lshl_b32 s40, s3, 12
	s_add_i32 s44, s40, 0
	s_add_i32 s45, s40, 0x8000
	s_add_i32 s46, s40, 0x10000
	s_add_i32 s47, s40, 0x18000
	v_lshrrev_b32_e32 v2, 4, v1
	v_and_b32_e32 v0, 7, v1
	v_xor_b32_e32 v2, v2, v0
	v_lshlrev_b32_e32 v2, 4, v2
	v_lshrrev_b32_e32 v0, 3, v1
	v_lshlrev_b32_e32 v0, 11, v0
	v_add_u32_e32 v232, v2, v0
	v_xor_b32_e32 v233, 64, v232
	v_and_b32_e32 v0, 31, v1
	v_lshrrev_b32_e32 v2, 1, v0
	v_and_b32_e32 v2, 7, v2
	v_lshrrev_b32_e32 v1, 5, v1
	v_xor_b32_e32 v2, v2, v1
	s_and_b32 s0, s3, 3
	s_lshr_b32 s1, s3, 2
	s_lshl_b32 s10, s0, 13
	s_lshl_b32 s11, s1, 13
	s_add_i32 s11, s11, 0x10000
	s_lshl_b32 s0, s0, 6
	v_add_u32_e32 v234, s0, v0
	s_lshl_b32 s1, s1, 7
	v_lshl_add_u32 v235, v1, 4, s1
	v_lshlrev_b32_e32 v0, 7, v0
	v_xor_b32_e32 v214, 0, v2
	v_lshl_add_u32 v214, v214, 4, v0
	v_add_u32_e32 v210, s10, v214
	v_add_u32_e32 v214, s11, v214
	v_xor_b32_e32 v215, 2, v2
	v_lshl_add_u32 v215, v215, 4, v0
	v_add_u32_e32 v211, s10, v215
	v_add_u32_e32 v215, s11, v215
	v_xor_b32_e32 v216, 4, v2
	v_lshl_add_u32 v216, v216, 4, v0
	v_add_u32_e32 v212, s10, v216
	v_add_u32_e32 v216, s11, v216
	v_xor_b32_e32 v217, 6, v2
	v_lshl_add_u32 v217, v217, 4, v0
	v_add_u32_e32 v213, s10, v217
	v_add_u32_e32 v217, s11, v217
	s_mul_i32 s0, s101, 0x5556
	s_lshr_b32 s26, s0, 16
	s_mul_i32 s0, s26, 3
	s_sub_i32 s0, s101, s0
	s_mul_i32 s0, s0, 6
	s_add_i32 s0, s0, s41
	s_cmpk_lt_u32 s101, 0xc6
	s_cbranch_scc1 .Lpp_col1
	s_mul_i32 s1, s41, 11
	s_add_i32 s1, s1, s101
	s_sub_i32 s26, s1, 0xc6
	s_movk_i32 s0, 18
.Lpp_col1:
	s_lshl_b32 s1, s0, 1
	s_cmp_gt_u32 s0, 1
	s_cselect_b32 s2, 4, 0
	s_add_i32 s2, s1, s2
	v_readlane_b32 s4, v241, 26
	v_readlane_b32 s5, v241, 27
	s_lshl_b32 s0, s26, 19
	s_add_u32 s4, s4, s0
	s_addc_u32 s5, s5, 0
	s_lshl_b32 s0, s2, 18
	s_add_u32 s6, s18, s0
	s_addc_u32 s7, s19, 0
	s_add_u32 s68, s4, s13
	s_addc_u32 s69, s5, 0
	s_add_u32 s70, s68, 0x3c00
	s_addc_u32 s71, s69, 0
	s_add_u32 s72, s70, 0x3c00
	s_addc_u32 s73, s71, 0
	s_add_u32 s74, s72, 0x3c00
	s_addc_u32 s75, s73, 0
	s_add_u32 s76, s6, s13
	s_addc_u32 s77, s7, 0
	s_add_u32 s78, s76, 0x3c00
	s_addc_u32 s79, s77, 0
	s_add_u32 s80, s78, 0x3c00
	s_addc_u32 s81, s79, 0
	s_add_u32 s82, s80, 0x3c00
	s_addc_u32 s83, s81, 0
	v_mov_b32_e32 v208, v232
	v_mov_b32_e32 v209, v233
	s_mov_b32 m0, s44
	s_nop 0
	global_load_lds_dwordx4 v208, s[68:69]
	global_load_lds_dwordx4 v209, s[70:71] offset:1024
	global_load_lds_dwordx4 v208, s[72:73] offset:2048
	global_load_lds_dwordx4 v209, s[74:75] offset:3072
	s_mov_b32 m0, s46
	s_nop 0
	global_load_lds_dwordx4 v208, s[76:77]
	global_load_lds_dwordx4 v209, s[78:79] offset:1024
	global_load_lds_dwordx4 v208, s[80:81] offset:2048
	global_load_lds_dwordx4 v209, s[82:83] offset:3072
	v_add_u32_e32 v208, 0x80, v208
	v_add_u32_e32 v209, 0x80, v209
	s_lshl_b32 s12, s26, 8
	v_add_u32_e32 v0, s12, v234
	v_mul_u32_u24_e32 v0, 0x2a00, v0
	s_lshl_b32 s12, s2, 8
	v_add3_u32 v218, v0, v235, s12
	v_add_u32_e32 v219, 0x54000, v218
	s_waitcnt vmcnt(0)
	s_branch .Lpp_k0
.Lpp_loop:
	s_lshl_b32 s12, s26, 8
	v_add_u32_e32 v0, s12, v234
	v_mul_u32_u24_e32 v0, 0x2a00, v0
	s_lshl_b32 s12, s2, 8
	v_add3_u32 v218, v0, v235, s12
	v_add_u32_e32 v219, 0x54000, v218
	s_waitcnt vmcnt(16)
; #define MFMA32(a, b, c) __builtin_amdgcn_mfma_f32_32x32x16_bf16((a), (b), (c), 0, 0, 0)
; template <bool SWAP, class Epi>
; DI void gemm_tile(const u16* __restrict__ A, int lda, const u16* __restrict__ Bw, int ldb, int K, char* lds, Epi epi) {
;     ...
;   auto compute = [&](int st) {
;     const char* as = lds + st * GEMM_STAGE;
;     const char* bs = as + 36864;
; #pragma unroll
;     for (int ks = 0; ks < 4; ++ks) {
;       bf16x8 af[2], bfr[2];
; #pragma unroll
;       for (int mi = 0; mi < 2; ++mi) af[mi] = *(const bf16x8*)(as + ((wm * 64 + mi * 32 + r) * 72 + ks * 16 + 8 * h) * 2);
; #pragma unroll
;       for (int ni = 0; ni < 2; ++ni) bfr[ni] = *(const bf16x8*)(bs + ((wn * 64 + ni * 32 + r) * 72 + ks * 16 + 8 * h) * 2);
; #pragma unroll
;       for (int mi = 0; mi < 2; ++mi)
; #pragma unroll
;         for (int ni = 0; ni < 2; ++ni) {
;           if (SWAP) acc[mi][ni] = MFMA32(bfr[ni], af[mi], acc[mi][ni]);
;           else acc[mi][ni] = MFMA32(af[mi], bfr[ni], acc[mi][ni]);
;         }
;     }
;   };
;   gload(0, ra0, rb0);
;   lstore(0, ra0, rb0);
;   gload(1, ra1, rb1);
;   __syncthreads();
;   for (int kt = 0; kt < nk; kt += 2) {
;     if (kt + 2 < nk) gload(kt + 2, ra0, rb0);
;     compute(0);
;     lstore(1, ra1, rb1);
;     __syncthreads();
;     if (kt + 3 < nk) gload(kt + 3, ra1, rb1);
;     compute(1);
;     if (kt + 2 < nk) lstore(0, ra0, rb0);
;     __syncthreads();
.Lpp_k0:
	s_waitcnt lgkmcnt(0)
	s_barrier
	ds_read_b128 v[132:135], v210 offset:0
	ds_read_b128 v[136:139], v210 offset:4096
	ds_read_b128 v[140:143], v214 offset:0
	ds_read_b128 v[144:147], v214 offset:4096
	ds_read_b128 v[148:151], v214 offset:16384
	ds_read_b128 v[158:161], v214 offset:20480
	s_mov_b32 m0, s45
	s_nop 0
	global_load_lds_dwordx4 v208, s[68:69]
	global_load_lds_dwordx4 v209, s[70:71] offset:1024
	global_load_lds_dwordx4 v208, s[72:73] offset:2048
	global_load_lds_dwordx4 v209, s[74:75] offset:3072
	ds_read_b128 v[162:165], v211 offset:0
	ds_read_b128 v[168:171], v211 offset:4096
	ds_read_b128 v[172:175], v215 offset:0
	ds_read_b128 v[176:179], v215 offset:4096
	ds_read_b128 v[180:183], v215 offset:16384
	ds_read_b128 v[184:187], v215 offset:20480
	s_waitcnt lgkmcnt(6)
	v_mfma_f32_32x32x16_bf16 v[4:19], v[140:143], v[132:135], 0
	v_mfma_f32_32x32x16_bf16 v[68:83], v[140:143], v[136:139], 0
	v_mfma_f32_32x32x16_bf16 v[20:35], v[144:147], v[132:135], 0
	v_mfma_f32_32x32x16_bf16 v[84:99], v[144:147], v[136:139], 0
	v_mfma_f32_32x32x16_bf16 v[36:51], v[148:151], v[132:135], 0
	v_mfma_f32_32x32x16_bf16 v[100:115], v[148:151], v[136:139], 0
	v_mfma_f32_32x32x16_bf16 v[52:67], v[158:161], v[132:135], 0
	v_mfma_f32_32x32x16_bf16 v[116:131], v[158:161], v[136:139], 0
	s_mov_b32 m0, s47
	s_nop 0
	global_load_lds_dwordx4 v208, s[76:77]
	global_load_lds_dwordx4 v209, s[78:79] offset:1024
	global_load_lds_dwordx4 v208, s[80:81] offset:2048
	global_load_lds_dwordx4 v209, s[82:83] offset:3072
	v_add_u32_e32 v208, 0x80, v208
	v_add_u32_e32 v209, 0x80, v209
	ds_read_b128 v[132:135], v212 offset:0
	ds_read_b128 v[136:139], v212 offset:4096
	ds_read_b128 v[140:143], v216 offset:0
	ds_read_b128 v[144:147], v216 offset:4096
	ds_read_b128 v[148:151], v216 offset:16384
	ds_read_b128 v[158:161], v216 offset:20480
	s_waitcnt lgkmcnt(6)
	v_mfma_f32_32x32x16_bf16 v[4:19], v[172:175], v[162:165], v[4:19]
	v_mfma_f32_32x32x16_bf16 v[68:83], v[172:175], v[168:171], v[68:83]
	v_mfma_f32_32x32x16_bf16 v[20:35], v[176:179], v[162:165], v[20:35]
	v_mfma_f32_32x32x16_bf16 v[84:99], v[176:179], v[168:171], v[84:99]
	v_mfma_f32_32x32x16_bf16 v[36:51], v[180:183], v[162:165], v[36:51]
	v_mfma_f32_32x32x16_bf16 v[100:115], v[180:183], v[168:171], v[100:115]
	v_mfma_f32_32x32x16_bf16 v[52:67], v[184:187], v[162:165], v[52:67]
	v_mfma_f32_32x32x16_bf16 v[116:131], v[184:187], v[168:171], v[116:131]
	ds_read_b128 v[162:165], v213 offset:0
	ds_read_b128 v[168:171], v213 offset:4096
	ds_read_b128 v[172:175], v217 offset:0
	ds_read_b128 v[176:179], v217 offset:4096
	ds_read_b128 v[180:183], v217 offset:16384
	ds_read_b128 v[184:187], v217 offset:20480
	s_waitcnt lgkmcnt(6)
	v_mfma_f32_32x32x16_bf16 v[4:19], v[140:143], v[132:135], v[4:19]
	v_mfma_f32_32x32x16_bf16 v[68:83], v[140:143], v[136:139], v[68:83]
	v_mfma_f32_32x32x16_bf16 v[20:35], v[144:147], v[132:135], v[20:35]
	v_mfma_f32_32x32x16_bf16 v[84:99], v[144:147], v[136:139], v[84:99]
	v_mfma_f32_32x32x16_bf16 v[36:51], v[148:151], v[132:135], v[36:51]
	v_mfma_f32_32x32x16_bf16 v[100:115], v[148:151], v[136:139], v[100:115]
	v_mfma_f32_32x32x16_bf16 v[52:67], v[158:161], v[132:135], v[52:67]
	v_mfma_f32_32x32x16_bf16 v[116:131], v[158:161], v[136:139], v[116:131]
	s_waitcnt lgkmcnt(0)
	v_mfma_f32_32x32x16_bf16 v[4:19], v[172:175], v[162:165], v[4:19]
	v_mfma_f32_32x32x16_bf16 v[68:83], v[172:175], v[168:171], v[68:83]
	v_mfma_f32_32x32x16_bf16 v[20:35], v[176:179], v[162:165], v[20:35]
	v_mfma_f32_32x32x16_bf16 v[84:99], v[176:179], v[168:171], v[84:99]
	v_mfma_f32_32x32x16_bf16 v[36:51], v[180:183], v[162:165], v[36:51]
	v_mfma_f32_32x32x16_bf16 v[100:115], v[180:183], v[168:171], v[100:115]
	v_mfma_f32_32x32x16_bf16 v[52:67], v[184:187], v[162:165], v[52:67]
	v_mfma_f32_32x32x16_bf16 v[116:131], v[184:187], v[168:171], v[116:131]
	s_waitcnt vmcnt(0) lgkmcnt(0)
	s_barrier
	ds_read_b128 v[132:135], v210 offset:32768
	ds_read_b128 v[136:139], v210 offset:36864
	ds_read_b128 v[140:143], v214 offset:32768
	ds_read_b128 v[144:147], v214 offset:36864
	ds_read_b128 v[148:151], v214 offset:49152
	ds_read_b128 v[158:161], v214 offset:53248
	s_mov_b32 m0, s44
	s_nop 0
	global_load_lds_dwordx4 v208, s[68:69]
	global_load_lds_dwordx4 v209, s[70:71] offset:1024
	global_load_lds_dwordx4 v208, s[72:73] offset:2048
	global_load_lds_dwordx4 v209, s[74:75] offset:3072
	ds_read_b128 v[162:165], v211 offset:32768
	ds_read_b128 v[168:171], v211 offset:36864
	ds_read_b128 v[172:175], v215 offset:32768
	ds_read_b128 v[176:179], v215 offset:36864
	ds_read_b128 v[180:183], v215 offset:49152
	ds_read_b128 v[184:187], v215 offset:53248
	s_waitcnt lgkmcnt(6)
	v_mfma_f32_32x32x16_bf16 v[4:19], v[140:143], v[132:135], v[4:19]
	v_mfma_f32_32x32x16_bf16 v[68:83], v[140:143], v[136:139], v[68:83]
	v_mfma_f32_32x32x16_bf16 v[20:35], v[144:147], v[132:135], v[20:35]
	v_mfma_f32_32x32x16_bf16 v[84:99], v[144:147], v[136:139], v[84:99]
	v_mfma_f32_32x32x16_bf16 v[36:51], v[148:151], v[132:135], v[36:51]
	v_mfma_f32_32x32x16_bf16 v[100:115], v[148:151], v[136:139], v[100:115]
	v_mfma_f32_32x32x16_bf16 v[52:67], v[158:161], v[132:135], v[52:67]
	v_mfma_f32_32x32x16_bf16 v[116:131], v[158:161], v[136:139], v[116:131]
	s_mov_b32 m0, s46
	s_nop 0
	global_load_lds_dwordx4 v208, s[76:77]
	global_load_lds_dwordx4 v209, s[78:79] offset:1024
	global_load_lds_dwordx4 v208, s[80:81] offset:2048
	global_load_lds_dwordx4 v209, s[82:83] offset:3072
	v_add_u32_e32 v208, 0x80, v208
	v_add_u32_e32 v209, 0x80, v209
	ds_read_b128 v[132:135], v212 offset:32768
	ds_read_b128 v[136:139], v212 offset:36864
	ds_read_b128 v[140:143], v216 offset:32768
	ds_read_b128 v[144:147], v216 offset:36864
	ds_read_b128 v[148:151], v216 offset:49152
	ds_read_b128 v[158:161], v216 offset:53248
	s_waitcnt lgkmcnt(6)
; #define MFMA32(a, b, c) __builtin_amdgcn_mfma_f32_32x32x16_bf16((a), (b), (c), 0, 0, 0)
; template <bool SWAP, class Epi>
; DI void gemm_tile(const u16* __restrict__ A, int lda, const u16* __restrict__ Bw, int ldb, int K, char* lds, Epi epi) {
;     ...
;   auto compute = [&](int st) {
;     const char* as = lds + st * GEMM_STAGE;
;     const char* bs = as + 36864;
; #pragma unroll
;     for (int ks = 0; ks < 4; ++ks) {
;       bf16x8 af[2], bfr[2];
; #pragma unroll
;       for (int mi = 0; mi < 2; ++mi) af[mi] = *(const bf16x8*)(as + ((wm * 64 + mi * 32 + r) * 72 + ks * 16 + 8 * h) * 2);
; #pragma unroll
;       for (int ni = 0; ni < 2; ++ni) bfr[ni] = *(const bf16x8*)(bs + ((wn * 64 + ni * 32 + r) * 72 + ks * 16 + 8 * h) * 2);
; #pragma unroll
;       for (int mi = 0; mi < 2; ++mi)
; #pragma unroll
;         for (int ni = 0; ni < 2; ++ni) {
;           if (SWAP) acc[mi][ni] = MFMA32(bfr[ni], af[mi], acc[mi][ni]);
;           else acc[mi][ni] = MFMA32(af[mi], bfr[ni], acc[mi][ni]);
;         }
;     }
;   };
;   gload(0, ra0, rb0);
;   lstore(0, ra0, rb0);
;   gload(1, ra1, rb1);
;   __syncthreads();
;   for (int kt = 0; kt < nk; kt += 2) {
;     if (kt + 2 < nk) gload(kt + 2, ra0, rb0);
;     compute(0);
;     lstore(1, ra1, rb1);
;     __syncthreads();
;     if (kt + 3 < nk) gload(kt + 3, ra1, rb1);
;     compute(1);
;     if (kt + 2 < nk) lstore(0, ra0, rb0);
;     __syncthreads();
	v_mfma_f32_32x32x16_bf16 v[4:19], v[172:175], v[162:165], v[4:19]
	v_mfma_f32_32x32x16_bf16 v[68:83], v[172:175], v[168:171], v[68:83]
	v_mfma_f32_32x32x16_bf16 v[20:35], v[176:179], v[162:165], v[20:35]
	v_mfma_f32_32x32x16_bf16 v[84:99], v[176:179], v[168:171], v[84:99]
	v_mfma_f32_32x32x16_bf16 v[36:51], v[180:183], v[162:165], v[36:51]
	v_mfma_f32_32x32x16_bf16 v[100:115], v[180:183], v[168:171], v[100:115]
	v_mfma_f32_32x32x16_bf16 v[52:67], v[184:187], v[162:165], v[52:67]
	v_mfma_f32_32x32x16_bf16 v[116:131], v[184:187], v[168:171], v[116:131]
	ds_read_b128 v[162:165], v213 offset:32768
	ds_read_b128 v[168:171], v213 offset:36864
	ds_read_b128 v[172:175], v217 offset:32768
	ds_read_b128 v[176:179], v217 offset:36864
	ds_read_b128 v[180:183], v217 offset:49152
	ds_read_b128 v[184:187], v217 offset:53248
	s_waitcnt lgkmcnt(6)
	v_mfma_f32_32x32x16_bf16 v[4:19], v[140:143], v[132:135], v[4:19]
	v_mfma_f32_32x32x16_bf16 v[68:83], v[140:143], v[136:139], v[68:83]
	v_mfma_f32_32x32x16_bf16 v[20:35], v[144:147], v[132:135], v[20:35]
	v_mfma_f32_32x32x16_bf16 v[84:99], v[144:147], v[136:139], v[84:99]
	v_mfma_f32_32x32x16_bf16 v[36:51], v[148:151], v[132:135], v[36:51]
	v_mfma_f32_32x32x16_bf16 v[100:115], v[148:151], v[136:139], v[100:115]
	v_mfma_f32_32x32x16_bf16 v[52:67], v[158:161], v[132:135], v[52:67]
	v_mfma_f32_32x32x16_bf16 v[116:131], v[158:161], v[136:139], v[116:131]
	s_waitcnt lgkmcnt(0)
	v_mfma_f32_32x32x16_bf16 v[4:19], v[172:175], v[162:165], v[4:19]
	v_mfma_f32_32x32x16_bf16 v[68:83], v[172:175], v[168:171], v[68:83]
	v_mfma_f32_32x32x16_bf16 v[20:35], v[176:179], v[162:165], v[20:35]
	v_mfma_f32_32x32x16_bf16 v[84:99], v[176:179], v[168:171], v[84:99]
	v_mfma_f32_32x32x16_bf16 v[36:51], v[180:183], v[162:165], v[36:51]
	v_mfma_f32_32x32x16_bf16 v[100:115], v[180:183], v[168:171], v[100:115]
	v_mfma_f32_32x32x16_bf16 v[52:67], v[184:187], v[162:165], v[52:67]
	v_mfma_f32_32x32x16_bf16 v[116:131], v[184:187], v[168:171], v[116:131]
	s_waitcnt vmcnt(0) lgkmcnt(0)
	s_barrier
	ds_read_b128 v[132:135], v210 offset:0
	ds_read_b128 v[136:139], v210 offset:4096
	ds_read_b128 v[140:143], v214 offset:0
	ds_read_b128 v[144:147], v214 offset:4096
	ds_read_b128 v[148:151], v214 offset:16384
	ds_read_b128 v[158:161], v214 offset:20480
	s_mov_b32 m0, s45
	s_nop 0
	global_load_lds_dwordx4 v208, s[68:69]
	global_load_lds_dwordx4 v209, s[70:71] offset:1024
	global_load_lds_dwordx4 v208, s[72:73] offset:2048
	global_load_lds_dwordx4 v209, s[74:75] offset:3072
	ds_read_b128 v[162:165], v211 offset:0
	ds_read_b128 v[168:171], v211 offset:4096
	ds_read_b128 v[172:175], v215 offset:0
	ds_read_b128 v[176:179], v215 offset:4096
	ds_read_b128 v[180:183], v215 offset:16384
	ds_read_b128 v[184:187], v215 offset:20480
	s_waitcnt lgkmcnt(6)
	v_mfma_f32_32x32x16_bf16 v[4:19], v[140:143], v[132:135], v[4:19]
	v_mfma_f32_32x32x16_bf16 v[68:83], v[140:143], v[136:139], v[68:83]
	v_mfma_f32_32x32x16_bf16 v[20:35], v[144:147], v[132:135], v[20:35]
	v_mfma_f32_32x32x16_bf16 v[84:99], v[144:147], v[136:139], v[84:99]
	v_mfma_f32_32x32x16_bf16 v[36:51], v[148:151], v[132:135], v[36:51]
	v_mfma_f32_32x32x16_bf16 v[100:115], v[148:151], v[136:139], v[100:115]
	v_mfma_f32_32x32x16_bf16 v[52:67], v[158:161], v[132:135], v[52:67]
	v_mfma_f32_32x32x16_bf16 v[116:131], v[158:161], v[136:139], v[116:131]
	s_mov_b32 m0, s47
	s_nop 0
	global_load_lds_dwordx4 v208, s[76:77]
	global_load_lds_dwordx4 v209, s[78:79] offset:1024
	global_load_lds_dwordx4 v208, s[80:81] offset:2048
	global_load_lds_dwordx4 v209, s[82:83] offset:3072
	v_add_u32_e32 v208, 0x80, v208
	v_add_u32_e32 v209, 0x80, v209
	ds_read_b128 v[132:135], v212 offset:0
	ds_read_b128 v[136:139], v212 offset:4096
	ds_read_b128 v[140:143], v216 offset:0
	ds_read_b128 v[144:147], v216 offset:4096
	ds_read_b128 v[148:151], v216 offset:16384
	ds_read_b128 v[158:161], v216 offset:20480
	s_waitcnt lgkmcnt(6)
	v_mfma_f32_32x32x16_bf16 v[4:19], v[172:175], v[162:165], v[4:19]
	v_mfma_f32_32x32x16_bf16 v[68:83], v[172:175], v[168:171], v[68:83]
	v_mfma_f32_32x32x16_bf16 v[20:35], v[176:179], v[162:165], v[20:35]
	v_mfma_f32_32x32x16_bf16 v[84:99], v[176:179], v[168:171], v[84:99]
	v_mfma_f32_32x32x16_bf16 v[36:51], v[180:183], v[162:165], v[36:51]
	v_mfma_f32_32x32x16_bf16 v[100:115], v[180:183], v[168:171], v[100:115]
	v_mfma_f32_32x32x16_bf16 v[52:67], v[184:187], v[162:165], v[52:67]
	v_mfma_f32_32x32x16_bf16 v[116:131], v[184:187], v[168:171], v[116:131]
	ds_read_b128 v[162:165], v213 offset:0
	ds_read_b128 v[168:171], v213 offset:4096
	ds_read_b128 v[172:175], v217 offset:0
	ds_read_b128 v[176:179], v217 offset:4096
	ds_read_b128 v[180:183], v217 offset:16384
	ds_read_b128 v[184:187], v217 offset:20480
	s_waitcnt lgkmcnt(6)
	v_mfma_f32_32x32x16_bf16 v[4:19], v[140:143], v[132:135], v[4:19]
	v_mfma_f32_32x32x16_bf16 v[68:83], v[140:143], v[136:139], v[68:83]
	v_mfma_f32_32x32x16_bf16 v[20:35], v[144:147], v[132:135], v[20:35]
	v_mfma_f32_32x32x16_bf16 v[84:99], v[144:147], v[136:139], v[84:99]
	v_mfma_f32_32x32x16_bf16 v[36:51], v[148:151], v[132:135], v[36:51]
	v_mfma_f32_32x32x16_bf16 v[100:115], v[148:151], v[136:139], v[100:115]
	v_mfma_f32_32x32x16_bf16 v[52:67], v[158:161], v[132:135], v[52:67]
	v_mfma_f32_32x32x16_bf16 v[116:131], v[158:161], v[136:139], v[116:131]
	s_waitcnt lgkmcnt(0)
	v_mfma_f32_32x32x16_bf16 v[4:19], v[172:175], v[162:165], v[4:19]
	v_mfma_f32_32x32x16_bf16 v[68:83], v[172:175], v[168:171], v[68:83]
	v_mfma_f32_32x32x16_bf16 v[20:35], v[176:179], v[162:165], v[20:35]
	v_mfma_f32_32x32x16_bf16 v[84:99], v[176:179], v[168:171], v[84:99]
	v_mfma_f32_32x32x16_bf16 v[36:51], v[180:183], v[162:165], v[36:51]
	v_mfma_f32_32x32x16_bf16 v[100:115], v[180:183], v[168:171], v[100:115]
	v_mfma_f32_32x32x16_bf16 v[52:67], v[184:187], v[162:165], v[52:67]
	v_mfma_f32_32x32x16_bf16 v[116:131], v[184:187], v[168:171], v[116:131]
	s_waitcnt vmcnt(0) lgkmcnt(0)
	s_barrier
; #define MFMA32(a, b, c) __builtin_amdgcn_mfma_f32_32x32x16_bf16((a), (b), (c), 0, 0, 0)
; template <bool SWAP, class Epi>
; DI void gemm_tile(const u16* __restrict__ A, int lda, const u16* __restrict__ Bw, int ldb, int K, char* lds, Epi epi) {
;     ...
;   auto compute = [&](int st) {
;     const char* as = lds + st * GEMM_STAGE;
;     const char* bs = as + 36864;
; #pragma unroll
;     for (int ks = 0; ks < 4; ++ks) {
;       bf16x8 af[2], bfr[2];
; #pragma unroll
;       for (int mi = 0; mi < 2; ++mi) af[mi] = *(const bf16x8*)(as + ((wm * 64 + mi * 32 + r) * 72 + ks * 16 + 8 * h) * 2);
; #pragma unroll
;       for (int ni = 0; ni < 2; ++ni) bfr[ni] = *(const bf16x8*)(bs + ((wn * 64 + ni * 32 + r) * 72 + ks * 16 + 8 * h) * 2);
; #pragma unroll
;       for (int mi = 0; mi < 2; ++mi)
; #pragma unroll
;         for (int ni = 0; ni < 2; ++ni) {
;           if (SWAP) acc[mi][ni] = MFMA32(bfr[ni], af[mi], acc[mi][ni]);
;           else acc[mi][ni] = MFMA32(af[mi], bfr[ni], acc[mi][ni]);
;         }
;     }
;   };
;   gload(0, ra0, rb0);
;   lstore(0, ra0, rb0);
;   gload(1, ra1, rb1);
;   __syncthreads();
;   for (int kt = 0; kt < nk; kt += 2) {
;     if (kt + 2 < nk) gload(kt + 2, ra0, rb0);
;     compute(0);
;     lstore(1, ra1, rb1);
;     __syncthreads();
;     if (kt + 3 < nk) gload(kt + 3, ra1, rb1);
;     compute(1);
;     if (kt + 2 < nk) lstore(0, ra0, rb0);
;     __syncthreads();
	ds_read_b128 v[132:135], v210 offset:32768
	ds_read_b128 v[136:139], v210 offset:36864
	ds_read_b128 v[140:143], v214 offset:32768
	ds_read_b128 v[144:147], v214 offset:36864
	ds_read_b128 v[148:151], v214 offset:49152
	ds_read_b128 v[158:161], v214 offset:53248
	s_mov_b32 m0, s44
	s_nop 0
	global_load_lds_dwordx4 v208, s[68:69]
	global_load_lds_dwordx4 v209, s[70:71] offset:1024
	global_load_lds_dwordx4 v208, s[72:73] offset:2048
	global_load_lds_dwordx4 v209, s[74:75] offset:3072
	ds_read_b128 v[162:165], v211 offset:32768
	ds_read_b128 v[168:171], v211 offset:36864
	ds_read_b128 v[172:175], v215 offset:32768
	ds_read_b128 v[176:179], v215 offset:36864
	ds_read_b128 v[180:183], v215 offset:49152
	ds_read_b128 v[184:187], v215 offset:53248
	s_waitcnt lgkmcnt(6)
	v_mfma_f32_32x32x16_bf16 v[4:19], v[140:143], v[132:135], v[4:19]
	v_mfma_f32_32x32x16_bf16 v[68:83], v[140:143], v[136:139], v[68:83]
	v_mfma_f32_32x32x16_bf16 v[20:35], v[144:147], v[132:135], v[20:35]
	v_mfma_f32_32x32x16_bf16 v[84:99], v[144:147], v[136:139], v[84:99]
	v_mfma_f32_32x32x16_bf16 v[36:51], v[148:151], v[132:135], v[36:51]
	v_mfma_f32_32x32x16_bf16 v[100:115], v[148:151], v[136:139], v[100:115]
	v_mfma_f32_32x32x16_bf16 v[52:67], v[158:161], v[132:135], v[52:67]
	v_mfma_f32_32x32x16_bf16 v[116:131], v[158:161], v[136:139], v[116:131]
	s_mov_b32 m0, s46
	s_nop 0
	global_load_lds_dwordx4 v208, s[76:77]
	global_load_lds_dwordx4 v209, s[78:79] offset:1024
	global_load_lds_dwordx4 v208, s[80:81] offset:2048
	global_load_lds_dwordx4 v209, s[82:83] offset:3072
	v_add_u32_e32 v208, 0x80, v208
	v_add_u32_e32 v209, 0x80, v209
	ds_read_b128 v[132:135], v212 offset:32768
	ds_read_b128 v[136:139], v212 offset:36864
	ds_read_b128 v[140:143], v216 offset:32768
	ds_read_b128 v[144:147], v216 offset:36864
	ds_read_b128 v[148:151], v216 offset:49152
	ds_read_b128 v[158:161], v216 offset:53248
	s_waitcnt lgkmcnt(6)
	v_mfma_f32_32x32x16_bf16 v[4:19], v[172:175], v[162:165], v[4:19]
	v_mfma_f32_32x32x16_bf16 v[68:83], v[172:175], v[168:171], v[68:83]
	v_mfma_f32_32x32x16_bf16 v[20:35], v[176:179], v[162:165], v[20:35]
	v_mfma_f32_32x32x16_bf16 v[84:99], v[176:179], v[168:171], v[84:99]
	v_mfma_f32_32x32x16_bf16 v[36:51], v[180:183], v[162:165], v[36:51]
	v_mfma_f32_32x32x16_bf16 v[100:115], v[180:183], v[168:171], v[100:115]
	v_mfma_f32_32x32x16_bf16 v[52:67], v[184:187], v[162:165], v[52:67]
	v_mfma_f32_32x32x16_bf16 v[116:131], v[184:187], v[168:171], v[116:131]
	ds_read_b128 v[162:165], v213 offset:32768
	ds_read_b128 v[168:171], v213 offset:36864
	ds_read_b128 v[172:175], v217 offset:32768
	ds_read_b128 v[176:179], v217 offset:36864
	ds_read_b128 v[180:183], v217 offset:49152
	ds_read_b128 v[184:187], v217 offset:53248
	s_waitcnt lgkmcnt(6)
	v_mfma_f32_32x32x16_bf16 v[4:19], v[140:143], v[132:135], v[4:19]
	v_mfma_f32_32x32x16_bf16 v[68:83], v[140:143], v[136:139], v[68:83]
	v_mfma_f32_32x32x16_bf16 v[20:35], v[144:147], v[132:135], v[20:35]
	v_mfma_f32_32x32x16_bf16 v[84:99], v[144:147], v[136:139], v[84:99]
	v_mfma_f32_32x32x16_bf16 v[36:51], v[148:151], v[132:135], v[36:51]
	v_mfma_f32_32x32x16_bf16 v[100:115], v[148:151], v[136:139], v[100:115]
	v_mfma_f32_32x32x16_bf16 v[52:67], v[158:161], v[132:135], v[52:67]
	v_mfma_f32_32x32x16_bf16 v[116:131], v[158:161], v[136:139], v[116:131]
	s_waitcnt lgkmcnt(0)
	v_mfma_f32_32x32x16_bf16 v[4:19], v[172:175], v[162:165], v[4:19]
	v_mfma_f32_32x32x16_bf16 v[68:83], v[172:175], v[168:171], v[68:83]
	v_mfma_f32_32x32x16_bf16 v[20:35], v[176:179], v[162:165], v[20:35]
	v_mfma_f32_32x32x16_bf16 v[84:99], v[176:179], v[168:171], v[84:99]
	v_mfma_f32_32x32x16_bf16 v[36:51], v[180:183], v[162:165], v[36:51]
	v_mfma_f32_32x32x16_bf16 v[100:115], v[180:183], v[168:171], v[100:115]
	v_mfma_f32_32x32x16_bf16 v[52:67], v[184:187], v[162:165], v[52:67]
	v_mfma_f32_32x32x16_bf16 v[116:131], v[184:187], v[168:171], v[116:131]
	s_waitcnt vmcnt(0) lgkmcnt(0)
	s_barrier
	ds_read_b128 v[132:135], v210 offset:0
	ds_read_b128 v[136:139], v210 offset:4096
	ds_read_b128 v[140:143], v214 offset:0
	ds_read_b128 v[144:147], v214 offset:4096
	ds_read_b128 v[148:151], v214 offset:16384
	ds_read_b128 v[158:161], v214 offset:20480
	s_mov_b32 m0, s45
	s_nop 0
	global_load_lds_dwordx4 v208, s[68:69]
	global_load_lds_dwordx4 v209, s[70:71] offset:1024
	global_load_lds_dwordx4 v208, s[72:73] offset:2048
	global_load_lds_dwordx4 v209, s[74:75] offset:3072
	ds_read_b128 v[162:165], v211 offset:0
	ds_read_b128 v[168:171], v211 offset:4096
	ds_read_b128 v[172:175], v215 offset:0
	ds_read_b128 v[176:179], v215 offset:4096
	ds_read_b128 v[180:183], v215 offset:16384
	ds_read_b128 v[184:187], v215 offset:20480
	s_waitcnt lgkmcnt(6)
	v_mfma_f32_32x32x16_bf16 v[4:19], v[140:143], v[132:135], v[4:19]
	v_mfma_f32_32x32x16_bf16 v[68:83], v[140:143], v[136:139], v[68:83]
	v_mfma_f32_32x32x16_bf16 v[20:35], v[144:147], v[132:135], v[20:35]
	v_mfma_f32_32x32x16_bf16 v[84:99], v[144:147], v[136:139], v[84:99]
	v_mfma_f32_32x32x16_bf16 v[36:51], v[148:151], v[132:135], v[36:51]
	v_mfma_f32_32x32x16_bf16 v[100:115], v[148:151], v[136:139], v[100:115]
	v_mfma_f32_32x32x16_bf16 v[52:67], v[158:161], v[132:135], v[52:67]
	v_mfma_f32_32x32x16_bf16 v[116:131], v[158:161], v[136:139], v[116:131]
	s_mov_b32 m0, s47
	s_nop 0
	global_load_lds_dwordx4 v208, s[76:77]
	global_load_lds_dwordx4 v209, s[78:79] offset:1024
	global_load_lds_dwordx4 v208, s[80:81] offset:2048
	global_load_lds_dwordx4 v209, s[82:83] offset:3072
	v_add_u32_e32 v208, 0x80, v208
	v_add_u32_e32 v209, 0x80, v209
	ds_read_b128 v[132:135], v212 offset:0
	ds_read_b128 v[136:139], v212 offset:4096
	ds_read_b128 v[140:143], v216 offset:0
	ds_read_b128 v[144:147], v216 offset:4096
	ds_read_b128 v[148:151], v216 offset:16384
	ds_read_b128 v[158:161], v216 offset:20480
	s_waitcnt lgkmcnt(6)
; #define MFMA32(a, b, c) __builtin_amdgcn_mfma_f32_32x32x16_bf16((a), (b), (c), 0, 0, 0)
; template <bool SWAP, class Epi>
; DI void gemm_tile(const u16* __restrict__ A, int lda, const u16* __restrict__ Bw, int ldb, int K, char* lds, Epi epi) {
;     ...
;   auto compute = [&](int st) {
;     const char* as = lds + st * GEMM_STAGE;
;     const char* bs = as + 36864;
; #pragma unroll
;     for (int ks = 0; ks < 4; ++ks) {
;       bf16x8 af[2], bfr[2];
; #pragma unroll
;       for (int mi = 0; mi < 2; ++mi) af[mi] = *(const bf16x8*)(as + ((wm * 64 + mi * 32 + r) * 72 + ks * 16 + 8 * h) * 2);
; #pragma unroll
;       for (int ni = 0; ni < 2; ++ni) bfr[ni] = *(const bf16x8*)(bs + ((wn * 64 + ni * 32 + r) * 72 + ks * 16 + 8 * h) * 2);
; #pragma unroll
;       for (int mi = 0; mi < 2; ++mi)
; #pragma unroll
;         for (int ni = 0; ni < 2; ++ni) {
;           if (SWAP) acc[mi][ni] = MFMA32(bfr[ni], af[mi], acc[mi][ni]);
;           else acc[mi][ni] = MFMA32(af[mi], bfr[ni], acc[mi][ni]);
;         }
;     }
;   };
;   gload(0, ra0, rb0);
;   lstore(0, ra0, rb0);
;   gload(1, ra1, rb1);
;   __syncthreads();
;   for (int kt = 0; kt < nk; kt += 2) {
;     if (kt + 2 < nk) gload(kt + 2, ra0, rb0);
;     compute(0);
;     lstore(1, ra1, rb1);
;     __syncthreads();
;     if (kt + 3 < nk) gload(kt + 3, ra1, rb1);
;     compute(1);
;     if (kt + 2 < nk) lstore(0, ra0, rb0);
;     __syncthreads();
	v_mfma_f32_32x32x16_bf16 v[4:19], v[172:175], v[162:165], v[4:19]
	v_mfma_f32_32x32x16_bf16 v[68:83], v[172:175], v[168:171], v[68:83]
	v_mfma_f32_32x32x16_bf16 v[20:35], v[176:179], v[162:165], v[20:35]
	v_mfma_f32_32x32x16_bf16 v[84:99], v[176:179], v[168:171], v[84:99]
	v_mfma_f32_32x32x16_bf16 v[36:51], v[180:183], v[162:165], v[36:51]
	v_mfma_f32_32x32x16_bf16 v[100:115], v[180:183], v[168:171], v[100:115]
	v_mfma_f32_32x32x16_bf16 v[52:67], v[184:187], v[162:165], v[52:67]
	v_mfma_f32_32x32x16_bf16 v[116:131], v[184:187], v[168:171], v[116:131]
	ds_read_b128 v[162:165], v213 offset:0
	ds_read_b128 v[168:171], v213 offset:4096
	ds_read_b128 v[172:175], v217 offset:0
	ds_read_b128 v[176:179], v217 offset:4096
	ds_read_b128 v[180:183], v217 offset:16384
	ds_read_b128 v[184:187], v217 offset:20480
	s_waitcnt lgkmcnt(6)
	v_mfma_f32_32x32x16_bf16 v[4:19], v[140:143], v[132:135], v[4:19]
	v_mfma_f32_32x32x16_bf16 v[68:83], v[140:143], v[136:139], v[68:83]
	v_mfma_f32_32x32x16_bf16 v[20:35], v[144:147], v[132:135], v[20:35]
	v_mfma_f32_32x32x16_bf16 v[84:99], v[144:147], v[136:139], v[84:99]
	v_mfma_f32_32x32x16_bf16 v[36:51], v[148:151], v[132:135], v[36:51]
	v_mfma_f32_32x32x16_bf16 v[100:115], v[148:151], v[136:139], v[100:115]
	v_mfma_f32_32x32x16_bf16 v[52:67], v[158:161], v[132:135], v[52:67]
	v_mfma_f32_32x32x16_bf16 v[116:131], v[158:161], v[136:139], v[116:131]
	s_waitcnt lgkmcnt(0)
	v_mfma_f32_32x32x16_bf16 v[4:19], v[172:175], v[162:165], v[4:19]
	v_mfma_f32_32x32x16_bf16 v[68:83], v[172:175], v[168:171], v[68:83]
	v_mfma_f32_32x32x16_bf16 v[20:35], v[176:179], v[162:165], v[20:35]
	v_mfma_f32_32x32x16_bf16 v[84:99], v[176:179], v[168:171], v[84:99]
	v_mfma_f32_32x32x16_bf16 v[36:51], v[180:183], v[162:165], v[36:51]
	v_mfma_f32_32x32x16_bf16 v[100:115], v[180:183], v[168:171], v[100:115]
	v_mfma_f32_32x32x16_bf16 v[52:67], v[184:187], v[162:165], v[52:67]
	v_mfma_f32_32x32x16_bf16 v[116:131], v[184:187], v[168:171], v[116:131]
	s_waitcnt vmcnt(0) lgkmcnt(0)
	s_barrier
	ds_read_b128 v[132:135], v210 offset:32768
	ds_read_b128 v[136:139], v210 offset:36864
	ds_read_b128 v[140:143], v214 offset:32768
	ds_read_b128 v[144:147], v214 offset:36864
	ds_read_b128 v[148:151], v214 offset:49152
	ds_read_b128 v[158:161], v214 offset:53248
	s_mov_b32 m0, s44
	s_nop 0
	global_load_lds_dwordx4 v208, s[68:69]
	global_load_lds_dwordx4 v209, s[70:71] offset:1024
	global_load_lds_dwordx4 v208, s[72:73] offset:2048
	global_load_lds_dwordx4 v209, s[74:75] offset:3072
	ds_read_b128 v[162:165], v211 offset:32768
	ds_read_b128 v[168:171], v211 offset:36864
	ds_read_b128 v[172:175], v215 offset:32768
	ds_read_b128 v[176:179], v215 offset:36864
	ds_read_b128 v[180:183], v215 offset:49152
	ds_read_b128 v[184:187], v215 offset:53248
	s_waitcnt lgkmcnt(6)
	v_mfma_f32_32x32x16_bf16 v[4:19], v[140:143], v[132:135], v[4:19]
	v_mfma_f32_32x32x16_bf16 v[68:83], v[140:143], v[136:139], v[68:83]
	v_mfma_f32_32x32x16_bf16 v[20:35], v[144:147], v[132:135], v[20:35]
	v_mfma_f32_32x32x16_bf16 v[84:99], v[144:147], v[136:139], v[84:99]
	v_mfma_f32_32x32x16_bf16 v[36:51], v[148:151], v[132:135], v[36:51]
	v_mfma_f32_32x32x16_bf16 v[100:115], v[148:151], v[136:139], v[100:115]
	v_mfma_f32_32x32x16_bf16 v[52:67], v[158:161], v[132:135], v[52:67]
	v_mfma_f32_32x32x16_bf16 v[116:131], v[158:161], v[136:139], v[116:131]
	s_mov_b32 m0, s46
	s_nop 0
	global_load_lds_dwordx4 v208, s[76:77]
	global_load_lds_dwordx4 v209, s[78:79] offset:1024
	global_load_lds_dwordx4 v208, s[80:81] offset:2048
	global_load_lds_dwordx4 v209, s[82:83] offset:3072
	v_add_u32_e32 v208, 0x80, v208
	v_add_u32_e32 v209, 0x80, v209
	ds_read_b128 v[132:135], v212 offset:32768
	ds_read_b128 v[136:139], v212 offset:36864
	ds_read_b128 v[140:143], v216 offset:32768
	ds_read_b128 v[144:147], v216 offset:36864
	ds_read_b128 v[148:151], v216 offset:49152
	ds_read_b128 v[158:161], v216 offset:53248
	s_waitcnt lgkmcnt(6)
	v_mfma_f32_32x32x16_bf16 v[4:19], v[172:175], v[162:165], v[4:19]
	v_mfma_f32_32x32x16_bf16 v[68:83], v[172:175], v[168:171], v[68:83]
	v_mfma_f32_32x32x16_bf16 v[20:35], v[176:179], v[162:165], v[20:35]
	v_mfma_f32_32x32x16_bf16 v[84:99], v[176:179], v[168:171], v[84:99]
	v_mfma_f32_32x32x16_bf16 v[36:51], v[180:183], v[162:165], v[36:51]
	v_mfma_f32_32x32x16_bf16 v[100:115], v[180:183], v[168:171], v[100:115]
	v_mfma_f32_32x32x16_bf16 v[52:67], v[184:187], v[162:165], v[52:67]
	v_mfma_f32_32x32x16_bf16 v[116:131], v[184:187], v[168:171], v[116:131]
	ds_read_b128 v[162:165], v213 offset:32768
	ds_read_b128 v[168:171], v213 offset:36864
	ds_read_b128 v[172:175], v217 offset:32768
	ds_read_b128 v[176:179], v217 offset:36864
	ds_read_b128 v[180:183], v217 offset:49152
	ds_read_b128 v[184:187], v217 offset:53248
	s_waitcnt lgkmcnt(6)
	v_mfma_f32_32x32x16_bf16 v[4:19], v[140:143], v[132:135], v[4:19]
	v_mfma_f32_32x32x16_bf16 v[68:83], v[140:143], v[136:139], v[68:83]
	v_mfma_f32_32x32x16_bf16 v[20:35], v[144:147], v[132:135], v[20:35]
	v_mfma_f32_32x32x16_bf16 v[84:99], v[144:147], v[136:139], v[84:99]
	v_mfma_f32_32x32x16_bf16 v[36:51], v[148:151], v[132:135], v[36:51]
	v_mfma_f32_32x32x16_bf16 v[100:115], v[148:151], v[136:139], v[100:115]
	v_mfma_f32_32x32x16_bf16 v[52:67], v[158:161], v[132:135], v[52:67]
	v_mfma_f32_32x32x16_bf16 v[116:131], v[158:161], v[136:139], v[116:131]
	s_waitcnt lgkmcnt(0)
	v_mfma_f32_32x32x16_bf16 v[4:19], v[172:175], v[162:165], v[4:19]
	v_mfma_f32_32x32x16_bf16 v[68:83], v[172:175], v[168:171], v[68:83]
	v_mfma_f32_32x32x16_bf16 v[20:35], v[176:179], v[162:165], v[20:35]
	v_mfma_f32_32x32x16_bf16 v[84:99], v[176:179], v[168:171], v[84:99]
	v_mfma_f32_32x32x16_bf16 v[36:51], v[180:183], v[162:165], v[36:51]
	v_mfma_f32_32x32x16_bf16 v[100:115], v[180:183], v[168:171], v[100:115]
	v_mfma_f32_32x32x16_bf16 v[52:67], v[184:187], v[162:165], v[52:67]
	v_mfma_f32_32x32x16_bf16 v[116:131], v[184:187], v[168:171], v[116:131]
	s_waitcnt vmcnt(0) lgkmcnt(0)
	s_barrier
; #define MFMA32(a, b, c) __builtin_amdgcn_mfma_f32_32x32x16_bf16((a), (b), (c), 0, 0, 0)
; template <bool SWAP, class Epi>
; DI void gemm_tile(const u16* __restrict__ A, int lda, const u16* __restrict__ Bw, int ldb, int K, char* lds, Epi epi) {
;     ...
;   auto compute = [&](int st) {
;     const char* as = lds + st * GEMM_STAGE;
;     const char* bs = as + 36864;
; #pragma unroll
;     for (int ks = 0; ks < 4; ++ks) {
;       bf16x8 af[2], bfr[2];
; #pragma unroll
;       for (int mi = 0; mi < 2; ++mi) af[mi] = *(const bf16x8*)(as + ((wm * 64 + mi * 32 + r) * 72 + ks * 16 + 8 * h) * 2);
; #pragma unroll
;       for (int ni = 0; ni < 2; ++ni) bfr[ni] = *(const bf16x8*)(bs + ((wn * 64 + ni * 32 + r) * 72 + ks * 16 + 8 * h) * 2);
; #pragma unroll
;       for (int mi = 0; mi < 2; ++mi)
; #pragma unroll
;         for (int ni = 0; ni < 2; ++ni) {
;           if (SWAP) acc[mi][ni] = MFMA32(bfr[ni], af[mi], acc[mi][ni]);
;           else acc[mi][ni] = MFMA32(af[mi], bfr[ni], acc[mi][ni]);
;         }
;     }
;   };
;   gload(0, ra0, rb0);
;   lstore(0, ra0, rb0);
;   gload(1, ra1, rb1);
;   __syncthreads();
;   for (int kt = 0; kt < nk; kt += 2) {
;     if (kt + 2 < nk) gload(kt + 2, ra0, rb0);
;     compute(0);
;     lstore(1, ra1, rb1);
;     __syncthreads();
;     if (kt + 3 < nk) gload(kt + 3, ra1, rb1);
;     compute(1);
;     if (kt + 2 < nk) lstore(0, ra0, rb0);
;     __syncthreads();
	ds_read_b128 v[132:135], v210 offset:0
	ds_read_b128 v[136:139], v210 offset:4096
	ds_read_b128 v[140:143], v214 offset:0
	ds_read_b128 v[144:147], v214 offset:4096
	ds_read_b128 v[148:151], v214 offset:16384
	ds_read_b128 v[158:161], v214 offset:20480
	s_mov_b32 m0, s45
	s_nop 0
	global_load_lds_dwordx4 v208, s[68:69]
	global_load_lds_dwordx4 v209, s[70:71] offset:1024
	global_load_lds_dwordx4 v208, s[72:73] offset:2048
	global_load_lds_dwordx4 v209, s[74:75] offset:3072
	ds_read_b128 v[162:165], v211 offset:0
	ds_read_b128 v[168:171], v211 offset:4096
	ds_read_b128 v[172:175], v215 offset:0
	ds_read_b128 v[176:179], v215 offset:4096
	ds_read_b128 v[180:183], v215 offset:16384
	ds_read_b128 v[184:187], v215 offset:20480
	s_waitcnt lgkmcnt(6)
	v_mfma_f32_32x32x16_bf16 v[4:19], v[140:143], v[132:135], v[4:19]
	v_mfma_f32_32x32x16_bf16 v[68:83], v[140:143], v[136:139], v[68:83]
	v_mfma_f32_32x32x16_bf16 v[20:35], v[144:147], v[132:135], v[20:35]
	v_mfma_f32_32x32x16_bf16 v[84:99], v[144:147], v[136:139], v[84:99]
	v_mfma_f32_32x32x16_bf16 v[36:51], v[148:151], v[132:135], v[36:51]
	v_mfma_f32_32x32x16_bf16 v[100:115], v[148:151], v[136:139], v[100:115]
	v_mfma_f32_32x32x16_bf16 v[52:67], v[158:161], v[132:135], v[52:67]
	v_mfma_f32_32x32x16_bf16 v[116:131], v[158:161], v[136:139], v[116:131]
	s_mov_b32 m0, s47
	s_nop 0
	global_load_lds_dwordx4 v208, s[76:77]
	global_load_lds_dwordx4 v209, s[78:79] offset:1024
	global_load_lds_dwordx4 v208, s[80:81] offset:2048
	global_load_lds_dwordx4 v209, s[82:83] offset:3072
	v_add_u32_e32 v208, 0x80, v208
	v_add_u32_e32 v209, 0x80, v209
	ds_read_b128 v[132:135], v212 offset:0
	ds_read_b128 v[136:139], v212 offset:4096
	ds_read_b128 v[140:143], v216 offset:0
	ds_read_b128 v[144:147], v216 offset:4096
	ds_read_b128 v[148:151], v216 offset:16384
	ds_read_b128 v[158:161], v216 offset:20480
	s_waitcnt lgkmcnt(6)
	v_mfma_f32_32x32x16_bf16 v[4:19], v[172:175], v[162:165], v[4:19]
	v_mfma_f32_32x32x16_bf16 v[68:83], v[172:175], v[168:171], v[68:83]
	v_mfma_f32_32x32x16_bf16 v[20:35], v[176:179], v[162:165], v[20:35]
	v_mfma_f32_32x32x16_bf16 v[84:99], v[176:179], v[168:171], v[84:99]
	v_mfma_f32_32x32x16_bf16 v[36:51], v[180:183], v[162:165], v[36:51]
	v_mfma_f32_32x32x16_bf16 v[100:115], v[180:183], v[168:171], v[100:115]
	v_mfma_f32_32x32x16_bf16 v[52:67], v[184:187], v[162:165], v[52:67]
	v_mfma_f32_32x32x16_bf16 v[116:131], v[184:187], v[168:171], v[116:131]
	ds_read_b128 v[162:165], v213 offset:0
	ds_read_b128 v[168:171], v213 offset:4096
	ds_read_b128 v[172:175], v217 offset:0
	ds_read_b128 v[176:179], v217 offset:4096
	ds_read_b128 v[180:183], v217 offset:16384
	ds_read_b128 v[184:187], v217 offset:20480
	s_waitcnt lgkmcnt(6)
	v_mfma_f32_32x32x16_bf16 v[4:19], v[140:143], v[132:135], v[4:19]
	v_mfma_f32_32x32x16_bf16 v[68:83], v[140:143], v[136:139], v[68:83]
	v_mfma_f32_32x32x16_bf16 v[20:35], v[144:147], v[132:135], v[20:35]
	v_mfma_f32_32x32x16_bf16 v[84:99], v[144:147], v[136:139], v[84:99]
	v_mfma_f32_32x32x16_bf16 v[36:51], v[148:151], v[132:135], v[36:51]
	v_mfma_f32_32x32x16_bf16 v[100:115], v[148:151], v[136:139], v[100:115]
	v_mfma_f32_32x32x16_bf16 v[52:67], v[158:161], v[132:135], v[52:67]
	v_mfma_f32_32x32x16_bf16 v[116:131], v[158:161], v[136:139], v[116:131]
	s_waitcnt lgkmcnt(0)
	v_mfma_f32_32x32x16_bf16 v[4:19], v[172:175], v[162:165], v[4:19]
	v_mfma_f32_32x32x16_bf16 v[68:83], v[172:175], v[168:171], v[68:83]
	v_mfma_f32_32x32x16_bf16 v[20:35], v[176:179], v[162:165], v[20:35]
	v_mfma_f32_32x32x16_bf16 v[84:99], v[176:179], v[168:171], v[84:99]
	v_mfma_f32_32x32x16_bf16 v[36:51], v[180:183], v[162:165], v[36:51]
	v_mfma_f32_32x32x16_bf16 v[100:115], v[180:183], v[168:171], v[100:115]
	v_mfma_f32_32x32x16_bf16 v[52:67], v[184:187], v[162:165], v[52:67]
	v_mfma_f32_32x32x16_bf16 v[116:131], v[184:187], v[168:171], v[116:131]
	s_waitcnt vmcnt(0) lgkmcnt(0)
	s_barrier
	ds_read_b128 v[132:135], v210 offset:32768
	ds_read_b128 v[136:139], v210 offset:36864
	ds_read_b128 v[140:143], v214 offset:32768
	ds_read_b128 v[144:147], v214 offset:36864
	ds_read_b128 v[148:151], v214 offset:49152
	ds_read_b128 v[158:161], v214 offset:53248
	s_mov_b32 m0, s44
	s_nop 0
	global_load_lds_dwordx4 v208, s[68:69]
	global_load_lds_dwordx4 v209, s[70:71] offset:1024
	global_load_lds_dwordx4 v208, s[72:73] offset:2048
	global_load_lds_dwordx4 v209, s[74:75] offset:3072
	ds_read_b128 v[162:165], v211 offset:32768
	ds_read_b128 v[168:171], v211 offset:36864
	ds_read_b128 v[172:175], v215 offset:32768
	ds_read_b128 v[176:179], v215 offset:36864
	ds_read_b128 v[180:183], v215 offset:49152
	ds_read_b128 v[184:187], v215 offset:53248
	s_waitcnt lgkmcnt(6)
	v_mfma_f32_32x32x16_bf16 v[4:19], v[140:143], v[132:135], v[4:19]
	v_mfma_f32_32x32x16_bf16 v[68:83], v[140:143], v[136:139], v[68:83]
	v_mfma_f32_32x32x16_bf16 v[20:35], v[144:147], v[132:135], v[20:35]
	v_mfma_f32_32x32x16_bf16 v[84:99], v[144:147], v[136:139], v[84:99]
	v_mfma_f32_32x32x16_bf16 v[36:51], v[148:151], v[132:135], v[36:51]
	v_mfma_f32_32x32x16_bf16 v[100:115], v[148:151], v[136:139], v[100:115]
	v_mfma_f32_32x32x16_bf16 v[52:67], v[158:161], v[132:135], v[52:67]
	v_mfma_f32_32x32x16_bf16 v[116:131], v[158:161], v[136:139], v[116:131]
	s_mov_b32 m0, s46
	s_nop 0
	global_load_lds_dwordx4 v208, s[76:77]
	global_load_lds_dwordx4 v209, s[78:79] offset:1024
	global_load_lds_dwordx4 v208, s[80:81] offset:2048
	global_load_lds_dwordx4 v209, s[82:83] offset:3072
	v_add_u32_e32 v208, 0x80, v208
	v_add_u32_e32 v209, 0x80, v209
	ds_read_b128 v[132:135], v212 offset:32768
	ds_read_b128 v[136:139], v212 offset:36864
	ds_read_b128 v[140:143], v216 offset:32768
	ds_read_b128 v[144:147], v216 offset:36864
	ds_read_b128 v[148:151], v216 offset:49152
	ds_read_b128 v[158:161], v216 offset:53248
	s_waitcnt lgkmcnt(6)
; #define MFMA32(a, b, c) __builtin_amdgcn_mfma_f32_32x32x16_bf16((a), (b), (c), 0, 0, 0)
; template <bool SWAP, class Epi>
; DI void gemm_tile(const u16* __restrict__ A, int lda, const u16* __restrict__ Bw, int ldb, int K, char* lds, Epi epi) {
;     ...
;   auto compute = [&](int st) {
;     const char* as = lds + st * GEMM_STAGE;
;     const char* bs = as + 36864;
; #pragma unroll
;     for (int ks = 0; ks < 4; ++ks) {
;       bf16x8 af[2], bfr[2];
; #pragma unroll
;       for (int mi = 0; mi < 2; ++mi) af[mi] = *(const bf16x8*)(as + ((wm * 64 + mi * 32 + r) * 72 + ks * 16 + 8 * h) * 2);
; #pragma unroll
;       for (int ni = 0; ni < 2; ++ni) bfr[ni] = *(const bf16x8*)(bs + ((wn * 64 + ni * 32 + r) * 72 + ks * 16 + 8 * h) * 2);
; #pragma unroll
;       for (int mi = 0; mi < 2; ++mi)
; #pragma unroll
;         for (int ni = 0; ni < 2; ++ni) {
;           if (SWAP) acc[mi][ni] = MFMA32(bfr[ni], af[mi], acc[mi][ni]);
;           else acc[mi][ni] = MFMA32(af[mi], bfr[ni], acc[mi][ni]);
;         }
;     }
;   };
;   gload(0, ra0, rb0);
;   lstore(0, ra0, rb0);
;   gload(1, ra1, rb1);
;   __syncthreads();
;   for (int kt = 0; kt < nk; kt += 2) {
;     if (kt + 2 < nk) gload(kt + 2, ra0, rb0);
;     compute(0);
;     lstore(1, ra1, rb1);
;     __syncthreads();
;     if (kt + 3 < nk) gload(kt + 3, ra1, rb1);
;     compute(1);
;     if (kt + 2 < nk) lstore(0, ra0, rb0);
;     __syncthreads();
	v_mfma_f32_32x32x16_bf16 v[4:19], v[172:175], v[162:165], v[4:19]
	v_mfma_f32_32x32x16_bf16 v[68:83], v[172:175], v[168:171], v[68:83]
	v_mfma_f32_32x32x16_bf16 v[20:35], v[176:179], v[162:165], v[20:35]
	v_mfma_f32_32x32x16_bf16 v[84:99], v[176:179], v[168:171], v[84:99]
	v_mfma_f32_32x32x16_bf16 v[36:51], v[180:183], v[162:165], v[36:51]
	v_mfma_f32_32x32x16_bf16 v[100:115], v[180:183], v[168:171], v[100:115]
	v_mfma_f32_32x32x16_bf16 v[52:67], v[184:187], v[162:165], v[52:67]
	v_mfma_f32_32x32x16_bf16 v[116:131], v[184:187], v[168:171], v[116:131]
	ds_read_b128 v[162:165], v213 offset:32768
	ds_read_b128 v[168:171], v213 offset:36864
	ds_read_b128 v[172:175], v217 offset:32768
	ds_read_b128 v[176:179], v217 offset:36864
	ds_read_b128 v[180:183], v217 offset:49152
	ds_read_b128 v[184:187], v217 offset:53248
	s_waitcnt lgkmcnt(6)
	v_mfma_f32_32x32x16_bf16 v[4:19], v[140:143], v[132:135], v[4:19]
	v_mfma_f32_32x32x16_bf16 v[68:83], v[140:143], v[136:139], v[68:83]
	v_mfma_f32_32x32x16_bf16 v[20:35], v[144:147], v[132:135], v[20:35]
	v_mfma_f32_32x32x16_bf16 v[84:99], v[144:147], v[136:139], v[84:99]
	v_mfma_f32_32x32x16_bf16 v[36:51], v[148:151], v[132:135], v[36:51]
	v_mfma_f32_32x32x16_bf16 v[100:115], v[148:151], v[136:139], v[100:115]
	v_mfma_f32_32x32x16_bf16 v[52:67], v[158:161], v[132:135], v[52:67]
	v_mfma_f32_32x32x16_bf16 v[116:131], v[158:161], v[136:139], v[116:131]
	s_waitcnt lgkmcnt(0)
	v_mfma_f32_32x32x16_bf16 v[4:19], v[172:175], v[162:165], v[4:19]
	v_mfma_f32_32x32x16_bf16 v[68:83], v[172:175], v[168:171], v[68:83]
	v_mfma_f32_32x32x16_bf16 v[20:35], v[176:179], v[162:165], v[20:35]
	v_mfma_f32_32x32x16_bf16 v[84:99], v[176:179], v[168:171], v[84:99]
	v_mfma_f32_32x32x16_bf16 v[36:51], v[180:183], v[162:165], v[36:51]
	v_mfma_f32_32x32x16_bf16 v[100:115], v[180:183], v[168:171], v[100:115]
	v_mfma_f32_32x32x16_bf16 v[52:67], v[184:187], v[162:165], v[52:67]
	v_mfma_f32_32x32x16_bf16 v[116:131], v[184:187], v[168:171], v[116:131]
	s_waitcnt vmcnt(0) lgkmcnt(0)
	s_barrier
	ds_read_b128 v[132:135], v210 offset:0
	ds_read_b128 v[136:139], v210 offset:4096
	ds_read_b128 v[140:143], v214 offset:0
	ds_read_b128 v[144:147], v214 offset:4096
	ds_read_b128 v[148:151], v214 offset:16384
	ds_read_b128 v[158:161], v214 offset:20480
	s_mov_b32 m0, s45
	s_nop 0
	global_load_lds_dwordx4 v208, s[68:69]
	global_load_lds_dwordx4 v209, s[70:71] offset:1024
	global_load_lds_dwordx4 v208, s[72:73] offset:2048
	global_load_lds_dwordx4 v209, s[74:75] offset:3072
	ds_read_b128 v[162:165], v211 offset:0
	ds_read_b128 v[168:171], v211 offset:4096
	ds_read_b128 v[172:175], v215 offset:0
	ds_read_b128 v[176:179], v215 offset:4096
	ds_read_b128 v[180:183], v215 offset:16384
	ds_read_b128 v[184:187], v215 offset:20480
	s_waitcnt lgkmcnt(6)
	v_mfma_f32_32x32x16_bf16 v[4:19], v[140:143], v[132:135], v[4:19]
	v_mfma_f32_32x32x16_bf16 v[68:83], v[140:143], v[136:139], v[68:83]
	v_mfma_f32_32x32x16_bf16 v[20:35], v[144:147], v[132:135], v[20:35]
	v_mfma_f32_32x32x16_bf16 v[84:99], v[144:147], v[136:139], v[84:99]
	v_mfma_f32_32x32x16_bf16 v[36:51], v[148:151], v[132:135], v[36:51]
	v_mfma_f32_32x32x16_bf16 v[100:115], v[148:151], v[136:139], v[100:115]
	v_mfma_f32_32x32x16_bf16 v[52:67], v[158:161], v[132:135], v[52:67]
	v_mfma_f32_32x32x16_bf16 v[116:131], v[158:161], v[136:139], v[116:131]
	s_mov_b32 m0, s47
	s_nop 0
	global_load_lds_dwordx4 v208, s[76:77]
	global_load_lds_dwordx4 v209, s[78:79] offset:1024
	global_load_lds_dwordx4 v208, s[80:81] offset:2048
	global_load_lds_dwordx4 v209, s[82:83] offset:3072
	v_add_u32_e32 v208, 0x80, v208
	v_add_u32_e32 v209, 0x80, v209
	ds_read_b128 v[132:135], v212 offset:0
	ds_read_b128 v[136:139], v212 offset:4096
	ds_read_b128 v[140:143], v216 offset:0
	ds_read_b128 v[144:147], v216 offset:4096
	ds_read_b128 v[148:151], v216 offset:16384
	ds_read_b128 v[158:161], v216 offset:20480
	s_waitcnt lgkmcnt(6)
	v_mfma_f32_32x32x16_bf16 v[4:19], v[172:175], v[162:165], v[4:19]
	v_mfma_f32_32x32x16_bf16 v[68:83], v[172:175], v[168:171], v[68:83]
	v_mfma_f32_32x32x16_bf16 v[20:35], v[176:179], v[162:165], v[20:35]
	v_mfma_f32_32x32x16_bf16 v[84:99], v[176:179], v[168:171], v[84:99]
	v_mfma_f32_32x32x16_bf16 v[36:51], v[180:183], v[162:165], v[36:51]
	v_mfma_f32_32x32x16_bf16 v[100:115], v[180:183], v[168:171], v[100:115]
	v_mfma_f32_32x32x16_bf16 v[52:67], v[184:187], v[162:165], v[52:67]
	v_mfma_f32_32x32x16_bf16 v[116:131], v[184:187], v[168:171], v[116:131]
	ds_read_b128 v[162:165], v213 offset:0
	ds_read_b128 v[168:171], v213 offset:4096
	ds_read_b128 v[172:175], v217 offset:0
	ds_read_b128 v[176:179], v217 offset:4096
	ds_read_b128 v[180:183], v217 offset:16384
	ds_read_b128 v[184:187], v217 offset:20480
	s_waitcnt lgkmcnt(6)
	v_mfma_f32_32x32x16_bf16 v[4:19], v[140:143], v[132:135], v[4:19]
	v_mfma_f32_32x32x16_bf16 v[68:83], v[140:143], v[136:139], v[68:83]
	v_mfma_f32_32x32x16_bf16 v[20:35], v[144:147], v[132:135], v[20:35]
	v_mfma_f32_32x32x16_bf16 v[84:99], v[144:147], v[136:139], v[84:99]
	v_mfma_f32_32x32x16_bf16 v[36:51], v[148:151], v[132:135], v[36:51]
	v_mfma_f32_32x32x16_bf16 v[100:115], v[148:151], v[136:139], v[100:115]
	v_mfma_f32_32x32x16_bf16 v[52:67], v[158:161], v[132:135], v[52:67]
	v_mfma_f32_32x32x16_bf16 v[116:131], v[158:161], v[136:139], v[116:131]
	s_waitcnt lgkmcnt(0)
	v_mfma_f32_32x32x16_bf16 v[4:19], v[172:175], v[162:165], v[4:19]
	v_mfma_f32_32x32x16_bf16 v[68:83], v[172:175], v[168:171], v[68:83]
	v_mfma_f32_32x32x16_bf16 v[20:35], v[176:179], v[162:165], v[20:35]
	v_mfma_f32_32x32x16_bf16 v[84:99], v[176:179], v[168:171], v[84:99]
	v_mfma_f32_32x32x16_bf16 v[36:51], v[180:183], v[162:165], v[36:51]
	v_mfma_f32_32x32x16_bf16 v[100:115], v[180:183], v[168:171], v[100:115]
	v_mfma_f32_32x32x16_bf16 v[52:67], v[184:187], v[162:165], v[52:67]
	v_mfma_f32_32x32x16_bf16 v[116:131], v[184:187], v[168:171], v[116:131]
	s_waitcnt vmcnt(0) lgkmcnt(0)
	s_barrier
; #define MFMA32(a, b, c) __builtin_amdgcn_mfma_f32_32x32x16_bf16((a), (b), (c), 0, 0, 0)
; template <bool SWAP, class Epi>
; DI void gemm_tile(const u16* __restrict__ A, int lda, const u16* __restrict__ Bw, int ldb, int K, char* lds, Epi epi) {
;     ...
;   auto compute = [&](int st) {
;     const char* as = lds + st * GEMM_STAGE;
;     const char* bs = as + 36864;
; #pragma unroll
;     for (int ks = 0; ks < 4; ++ks) {
;       bf16x8 af[2], bfr[2];
; #pragma unroll
;       for (int mi = 0; mi < 2; ++mi) af[mi] = *(const bf16x8*)(as + ((wm * 64 + mi * 32 + r) * 72 + ks * 16 + 8 * h) * 2);
; #pragma unroll
;       for (int ni = 0; ni < 2; ++ni) bfr[ni] = *(const bf16x8*)(bs + ((wn * 64 + ni * 32 + r) * 72 + ks * 16 + 8 * h) * 2);
; #pragma unroll
;       for (int mi = 0; mi < 2; ++mi)
; #pragma unroll
;         for (int ni = 0; ni < 2; ++ni) {
;           if (SWAP) acc[mi][ni] = MFMA32(bfr[ni], af[mi], acc[mi][ni]);
;           else acc[mi][ni] = MFMA32(af[mi], bfr[ni], acc[mi][ni]);
;         }
;     }
;   };
;   gload(0, ra0, rb0);
;   lstore(0, ra0, rb0);
;   gload(1, ra1, rb1);
;   __syncthreads();
;   for (int kt = 0; kt < nk; kt += 2) {
;     if (kt + 2 < nk) gload(kt + 2, ra0, rb0);
;     compute(0);
;     lstore(1, ra1, rb1);
;     __syncthreads();
;     if (kt + 3 < nk) gload(kt + 3, ra1, rb1);
;     compute(1);
;     if (kt + 2 < nk) lstore(0, ra0, rb0);
;     __syncthreads();
	ds_read_b128 v[132:135], v210 offset:32768
	ds_read_b128 v[136:139], v210 offset:36864
	ds_read_b128 v[140:143], v214 offset:32768
	ds_read_b128 v[144:147], v214 offset:36864
	ds_read_b128 v[148:151], v214 offset:49152
	ds_read_b128 v[158:161], v214 offset:53248
	s_mov_b32 m0, s44
	s_nop 0
	global_load_lds_dwordx4 v208, s[68:69]
	global_load_lds_dwordx4 v209, s[70:71] offset:1024
	global_load_lds_dwordx4 v208, s[72:73] offset:2048
	global_load_lds_dwordx4 v209, s[74:75] offset:3072
	ds_read_b128 v[162:165], v211 offset:32768
	ds_read_b128 v[168:171], v211 offset:36864
	ds_read_b128 v[172:175], v215 offset:32768
	ds_read_b128 v[176:179], v215 offset:36864
	ds_read_b128 v[180:183], v215 offset:49152
	ds_read_b128 v[184:187], v215 offset:53248
	s_waitcnt lgkmcnt(6)
	v_mfma_f32_32x32x16_bf16 v[4:19], v[140:143], v[132:135], v[4:19]
	v_mfma_f32_32x32x16_bf16 v[68:83], v[140:143], v[136:139], v[68:83]
	v_mfma_f32_32x32x16_bf16 v[20:35], v[144:147], v[132:135], v[20:35]
	v_mfma_f32_32x32x16_bf16 v[84:99], v[144:147], v[136:139], v[84:99]
	v_mfma_f32_32x32x16_bf16 v[36:51], v[148:151], v[132:135], v[36:51]
	v_mfma_f32_32x32x16_bf16 v[100:115], v[148:151], v[136:139], v[100:115]
	v_mfma_f32_32x32x16_bf16 v[52:67], v[158:161], v[132:135], v[52:67]
	v_mfma_f32_32x32x16_bf16 v[116:131], v[158:161], v[136:139], v[116:131]
	s_mov_b32 m0, s46
	s_nop 0
	global_load_lds_dwordx4 v208, s[76:77]
	global_load_lds_dwordx4 v209, s[78:79] offset:1024
	global_load_lds_dwordx4 v208, s[80:81] offset:2048
	global_load_lds_dwordx4 v209, s[82:83] offset:3072
	v_add_u32_e32 v208, 0x80, v208
	v_add_u32_e32 v209, 0x80, v209
	ds_read_b128 v[132:135], v212 offset:32768
	ds_read_b128 v[136:139], v212 offset:36864
	ds_read_b128 v[140:143], v216 offset:32768
	ds_read_b128 v[144:147], v216 offset:36864
	ds_read_b128 v[148:151], v216 offset:49152
	ds_read_b128 v[158:161], v216 offset:53248
	s_waitcnt lgkmcnt(6)
	v_mfma_f32_32x32x16_bf16 v[4:19], v[172:175], v[162:165], v[4:19]
	v_mfma_f32_32x32x16_bf16 v[68:83], v[172:175], v[168:171], v[68:83]
	v_mfma_f32_32x32x16_bf16 v[20:35], v[176:179], v[162:165], v[20:35]
	v_mfma_f32_32x32x16_bf16 v[84:99], v[176:179], v[168:171], v[84:99]
	v_mfma_f32_32x32x16_bf16 v[36:51], v[180:183], v[162:165], v[36:51]
	v_mfma_f32_32x32x16_bf16 v[100:115], v[180:183], v[168:171], v[100:115]
	v_mfma_f32_32x32x16_bf16 v[52:67], v[184:187], v[162:165], v[52:67]
	v_mfma_f32_32x32x16_bf16 v[116:131], v[184:187], v[168:171], v[116:131]
	ds_read_b128 v[162:165], v213 offset:32768
	ds_read_b128 v[168:171], v213 offset:36864
	ds_read_b128 v[172:175], v217 offset:32768
	ds_read_b128 v[176:179], v217 offset:36864
	ds_read_b128 v[180:183], v217 offset:49152
	ds_read_b128 v[184:187], v217 offset:53248
	s_waitcnt lgkmcnt(6)
	v_mfma_f32_32x32x16_bf16 v[4:19], v[140:143], v[132:135], v[4:19]
	v_mfma_f32_32x32x16_bf16 v[68:83], v[140:143], v[136:139], v[68:83]
	v_mfma_f32_32x32x16_bf16 v[20:35], v[144:147], v[132:135], v[20:35]
	v_mfma_f32_32x32x16_bf16 v[84:99], v[144:147], v[136:139], v[84:99]
	v_mfma_f32_32x32x16_bf16 v[36:51], v[148:151], v[132:135], v[36:51]
	v_mfma_f32_32x32x16_bf16 v[100:115], v[148:151], v[136:139], v[100:115]
	v_mfma_f32_32x32x16_bf16 v[52:67], v[158:161], v[132:135], v[52:67]
	v_mfma_f32_32x32x16_bf16 v[116:131], v[158:161], v[136:139], v[116:131]
	s_waitcnt lgkmcnt(0)
	v_mfma_f32_32x32x16_bf16 v[4:19], v[172:175], v[162:165], v[4:19]
	v_mfma_f32_32x32x16_bf16 v[68:83], v[172:175], v[168:171], v[68:83]
	v_mfma_f32_32x32x16_bf16 v[20:35], v[176:179], v[162:165], v[20:35]
	v_mfma_f32_32x32x16_bf16 v[84:99], v[176:179], v[168:171], v[84:99]
	v_mfma_f32_32x32x16_bf16 v[36:51], v[180:183], v[162:165], v[36:51]
	v_mfma_f32_32x32x16_bf16 v[100:115], v[180:183], v[168:171], v[100:115]
	v_mfma_f32_32x32x16_bf16 v[52:67], v[184:187], v[162:165], v[52:67]
	v_mfma_f32_32x32x16_bf16 v[116:131], v[184:187], v[168:171], v[116:131]
	s_waitcnt vmcnt(0) lgkmcnt(0)
	s_barrier
	ds_read_b128 v[132:135], v210 offset:0
	ds_read_b128 v[136:139], v210 offset:4096
	ds_read_b128 v[140:143], v214 offset:0
	ds_read_b128 v[144:147], v214 offset:4096
	ds_read_b128 v[148:151], v214 offset:16384
	ds_read_b128 v[158:161], v214 offset:20480
	s_mov_b32 m0, s45
	s_nop 0
	global_load_lds_dwordx4 v208, s[68:69]
	global_load_lds_dwordx4 v209, s[70:71] offset:1024
	global_load_lds_dwordx4 v208, s[72:73] offset:2048
	global_load_lds_dwordx4 v209, s[74:75] offset:3072
	ds_read_b128 v[162:165], v211 offset:0
	ds_read_b128 v[168:171], v211 offset:4096
	ds_read_b128 v[172:175], v215 offset:0
	ds_read_b128 v[176:179], v215 offset:4096
	ds_read_b128 v[180:183], v215 offset:16384
	ds_read_b128 v[184:187], v215 offset:20480
	s_waitcnt lgkmcnt(6)
	v_mfma_f32_32x32x16_bf16 v[4:19], v[140:143], v[132:135], v[4:19]
	v_mfma_f32_32x32x16_bf16 v[68:83], v[140:143], v[136:139], v[68:83]
	v_mfma_f32_32x32x16_bf16 v[20:35], v[144:147], v[132:135], v[20:35]
	v_mfma_f32_32x32x16_bf16 v[84:99], v[144:147], v[136:139], v[84:99]
	v_mfma_f32_32x32x16_bf16 v[36:51], v[148:151], v[132:135], v[36:51]
	v_mfma_f32_32x32x16_bf16 v[100:115], v[148:151], v[136:139], v[100:115]
	v_mfma_f32_32x32x16_bf16 v[52:67], v[158:161], v[132:135], v[52:67]
	v_mfma_f32_32x32x16_bf16 v[116:131], v[158:161], v[136:139], v[116:131]
	s_mov_b32 m0, s47
	s_nop 0
	global_load_lds_dwordx4 v208, s[76:77]
	global_load_lds_dwordx4 v209, s[78:79] offset:1024
	global_load_lds_dwordx4 v208, s[80:81] offset:2048
	global_load_lds_dwordx4 v209, s[82:83] offset:3072
	v_add_u32_e32 v208, 0x80, v208
	v_add_u32_e32 v209, 0x80, v209
	ds_read_b128 v[132:135], v212 offset:0
	ds_read_b128 v[136:139], v212 offset:4096
	ds_read_b128 v[140:143], v216 offset:0
	ds_read_b128 v[144:147], v216 offset:4096
	ds_read_b128 v[148:151], v216 offset:16384
	ds_read_b128 v[158:161], v216 offset:20480
	s_waitcnt lgkmcnt(6)
; #define MFMA32(a, b, c) __builtin_amdgcn_mfma_f32_32x32x16_bf16((a), (b), (c), 0, 0, 0)
; template <bool SWAP, class Epi>
; DI void gemm_tile(const u16* __restrict__ A, int lda, const u16* __restrict__ Bw, int ldb, int K, char* lds, Epi epi) {
;     ...
;   auto compute = [&](int st) {
;     const char* as = lds + st * GEMM_STAGE;
;     const char* bs = as + 36864;
; #pragma unroll
;     for (int ks = 0; ks < 4; ++ks) {
;       bf16x8 af[2], bfr[2];
; #pragma unroll
;       for (int mi = 0; mi < 2; ++mi) af[mi] = *(const bf16x8*)(as + ((wm * 64 + mi * 32 + r) * 72 + ks * 16 + 8 * h) * 2);
; #pragma unroll
;       for (int ni = 0; ni < 2; ++ni) bfr[ni] = *(const bf16x8*)(bs + ((wn * 64 + ni * 32 + r) * 72 + ks * 16 + 8 * h) * 2);
; #pragma unroll
;       for (int mi = 0; mi < 2; ++mi)
; #pragma unroll
;         for (int ni = 0; ni < 2; ++ni) {
;           if (SWAP) acc[mi][ni] = MFMA32(bfr[ni], af[mi], acc[mi][ni]);
;           else acc[mi][ni] = MFMA32(af[mi], bfr[ni], acc[mi][ni]);
;         }
;     }
;   };
;   gload(0, ra0, rb0);
;   lstore(0, ra0, rb0);
;   gload(1, ra1, rb1);
;   __syncthreads();
;   for (int kt = 0; kt < nk; kt += 2) {
;     if (kt + 2 < nk) gload(kt + 2, ra0, rb0);
;     compute(0);
;     lstore(1, ra1, rb1);
;     __syncthreads();
;     if (kt + 3 < nk) gload(kt + 3, ra1, rb1);
;     compute(1);
;     if (kt + 2 < nk) lstore(0, ra0, rb0);
;     __syncthreads();
	v_mfma_f32_32x32x16_bf16 v[4:19], v[172:175], v[162:165], v[4:19]
	v_mfma_f32_32x32x16_bf16 v[68:83], v[172:175], v[168:171], v[68:83]
	v_mfma_f32_32x32x16_bf16 v[20:35], v[176:179], v[162:165], v[20:35]
	v_mfma_f32_32x32x16_bf16 v[84:99], v[176:179], v[168:171], v[84:99]
	v_mfma_f32_32x32x16_bf16 v[36:51], v[180:183], v[162:165], v[36:51]
	v_mfma_f32_32x32x16_bf16 v[100:115], v[180:183], v[168:171], v[100:115]
	v_mfma_f32_32x32x16_bf16 v[52:67], v[184:187], v[162:165], v[52:67]
	v_mfma_f32_32x32x16_bf16 v[116:131], v[184:187], v[168:171], v[116:131]
	ds_read_b128 v[162:165], v213 offset:0
	ds_read_b128 v[168:171], v213 offset:4096
	ds_read_b128 v[172:175], v217 offset:0
	ds_read_b128 v[176:179], v217 offset:4096
	ds_read_b128 v[180:183], v217 offset:16384
	ds_read_b128 v[184:187], v217 offset:20480
	s_waitcnt lgkmcnt(6)
	v_mfma_f32_32x32x16_bf16 v[4:19], v[140:143], v[132:135], v[4:19]
	v_mfma_f32_32x32x16_bf16 v[68:83], v[140:143], v[136:139], v[68:83]
	v_mfma_f32_32x32x16_bf16 v[20:35], v[144:147], v[132:135], v[20:35]
	v_mfma_f32_32x32x16_bf16 v[84:99], v[144:147], v[136:139], v[84:99]
	v_mfma_f32_32x32x16_bf16 v[36:51], v[148:151], v[132:135], v[36:51]
	v_mfma_f32_32x32x16_bf16 v[100:115], v[148:151], v[136:139], v[100:115]
	v_mfma_f32_32x32x16_bf16 v[52:67], v[158:161], v[132:135], v[52:67]
	v_mfma_f32_32x32x16_bf16 v[116:131], v[158:161], v[136:139], v[116:131]
	s_waitcnt lgkmcnt(0)
	v_mfma_f32_32x32x16_bf16 v[4:19], v[172:175], v[162:165], v[4:19]
	v_mfma_f32_32x32x16_bf16 v[68:83], v[172:175], v[168:171], v[68:83]
	v_mfma_f32_32x32x16_bf16 v[20:35], v[176:179], v[162:165], v[20:35]
	v_mfma_f32_32x32x16_bf16 v[84:99], v[176:179], v[168:171], v[84:99]
	v_mfma_f32_32x32x16_bf16 v[36:51], v[180:183], v[162:165], v[36:51]
	v_mfma_f32_32x32x16_bf16 v[100:115], v[180:183], v[168:171], v[100:115]
	v_mfma_f32_32x32x16_bf16 v[52:67], v[184:187], v[162:165], v[52:67]
	v_mfma_f32_32x32x16_bf16 v[116:131], v[184:187], v[168:171], v[116:131]
	s_waitcnt vmcnt(0) lgkmcnt(0)
	s_barrier
	ds_read_b128 v[132:135], v210 offset:32768
	ds_read_b128 v[136:139], v210 offset:36864
	ds_read_b128 v[140:143], v214 offset:32768
	ds_read_b128 v[144:147], v214 offset:36864
	ds_read_b128 v[148:151], v214 offset:49152
	ds_read_b128 v[158:161], v214 offset:53248
	s_mov_b32 m0, s44
	s_nop 0
	global_load_lds_dwordx4 v208, s[68:69]
	global_load_lds_dwordx4 v209, s[70:71] offset:1024
	global_load_lds_dwordx4 v208, s[72:73] offset:2048
	global_load_lds_dwordx4 v209, s[74:75] offset:3072
	ds_read_b128 v[162:165], v211 offset:32768
	ds_read_b128 v[168:171], v211 offset:36864
	ds_read_b128 v[172:175], v215 offset:32768
	ds_read_b128 v[176:179], v215 offset:36864
	ds_read_b128 v[180:183], v215 offset:49152
	ds_read_b128 v[184:187], v215 offset:53248
	s_waitcnt lgkmcnt(6)
	v_mfma_f32_32x32x16_bf16 v[4:19], v[140:143], v[132:135], v[4:19]
	v_mfma_f32_32x32x16_bf16 v[68:83], v[140:143], v[136:139], v[68:83]
	v_mfma_f32_32x32x16_bf16 v[20:35], v[144:147], v[132:135], v[20:35]
	v_mfma_f32_32x32x16_bf16 v[84:99], v[144:147], v[136:139], v[84:99]
	v_mfma_f32_32x32x16_bf16 v[36:51], v[148:151], v[132:135], v[36:51]
	v_mfma_f32_32x32x16_bf16 v[100:115], v[148:151], v[136:139], v[100:115]
	v_mfma_f32_32x32x16_bf16 v[52:67], v[158:161], v[132:135], v[52:67]
	v_mfma_f32_32x32x16_bf16 v[116:131], v[158:161], v[136:139], v[116:131]
	s_mov_b32 m0, s46
	s_nop 0
	global_load_lds_dwordx4 v208, s[76:77]
	global_load_lds_dwordx4 v209, s[78:79] offset:1024
	global_load_lds_dwordx4 v208, s[80:81] offset:2048
	global_load_lds_dwordx4 v209, s[82:83] offset:3072
	v_add_u32_e32 v208, 0x80, v208
	v_add_u32_e32 v209, 0x80, v209
	ds_read_b128 v[132:135], v212 offset:32768
	ds_read_b128 v[136:139], v212 offset:36864
	ds_read_b128 v[140:143], v216 offset:32768
	ds_read_b128 v[144:147], v216 offset:36864
	ds_read_b128 v[148:151], v216 offset:49152
	ds_read_b128 v[158:161], v216 offset:53248
	s_waitcnt lgkmcnt(6)
	v_mfma_f32_32x32x16_bf16 v[4:19], v[172:175], v[162:165], v[4:19]
	v_mfma_f32_32x32x16_bf16 v[68:83], v[172:175], v[168:171], v[68:83]
	v_mfma_f32_32x32x16_bf16 v[20:35], v[176:179], v[162:165], v[20:35]
	v_mfma_f32_32x32x16_bf16 v[84:99], v[176:179], v[168:171], v[84:99]
	v_mfma_f32_32x32x16_bf16 v[36:51], v[180:183], v[162:165], v[36:51]
	v_mfma_f32_32x32x16_bf16 v[100:115], v[180:183], v[168:171], v[100:115]
	v_mfma_f32_32x32x16_bf16 v[52:67], v[184:187], v[162:165], v[52:67]
	v_mfma_f32_32x32x16_bf16 v[116:131], v[184:187], v[168:171], v[116:131]
	ds_read_b128 v[162:165], v213 offset:32768
	ds_read_b128 v[168:171], v213 offset:36864
	ds_read_b128 v[172:175], v217 offset:32768
	ds_read_b128 v[176:179], v217 offset:36864
	ds_read_b128 v[180:183], v217 offset:49152
	ds_read_b128 v[184:187], v217 offset:53248
	s_waitcnt lgkmcnt(6)
	v_mfma_f32_32x32x16_bf16 v[4:19], v[140:143], v[132:135], v[4:19]
	v_mfma_f32_32x32x16_bf16 v[68:83], v[140:143], v[136:139], v[68:83]
	v_mfma_f32_32x32x16_bf16 v[20:35], v[144:147], v[132:135], v[20:35]
	v_mfma_f32_32x32x16_bf16 v[84:99], v[144:147], v[136:139], v[84:99]
	v_mfma_f32_32x32x16_bf16 v[36:51], v[148:151], v[132:135], v[36:51]
	v_mfma_f32_32x32x16_bf16 v[100:115], v[148:151], v[136:139], v[100:115]
	v_mfma_f32_32x32x16_bf16 v[52:67], v[158:161], v[132:135], v[52:67]
	v_mfma_f32_32x32x16_bf16 v[116:131], v[158:161], v[136:139], v[116:131]
	s_waitcnt lgkmcnt(0)
	v_mfma_f32_32x32x16_bf16 v[4:19], v[172:175], v[162:165], v[4:19]
	v_mfma_f32_32x32x16_bf16 v[68:83], v[172:175], v[168:171], v[68:83]
	v_mfma_f32_32x32x16_bf16 v[20:35], v[176:179], v[162:165], v[20:35]
	v_mfma_f32_32x32x16_bf16 v[84:99], v[176:179], v[168:171], v[84:99]
	v_mfma_f32_32x32x16_bf16 v[36:51], v[180:183], v[162:165], v[36:51]
	v_mfma_f32_32x32x16_bf16 v[100:115], v[180:183], v[168:171], v[100:115]
	v_mfma_f32_32x32x16_bf16 v[52:67], v[184:187], v[162:165], v[52:67]
	v_mfma_f32_32x32x16_bf16 v[116:131], v[184:187], v[168:171], v[116:131]
	s_waitcnt vmcnt(0) lgkmcnt(0)
	s_barrier
; #define MFMA32(a, b, c) __builtin_amdgcn_mfma_f32_32x32x16_bf16((a), (b), (c), 0, 0, 0)
; template <bool SWAP, class Epi>
; DI void gemm_tile(const u16* __restrict__ A, int lda, const u16* __restrict__ Bw, int ldb, int K, char* lds, Epi epi) {
;     ...
;   auto compute = [&](int st) {
;     const char* as = lds + st * GEMM_STAGE;
;     const char* bs = as + 36864;
; #pragma unroll
;     for (int ks = 0; ks < 4; ++ks) {
;       bf16x8 af[2], bfr[2];
; #pragma unroll
;       for (int mi = 0; mi < 2; ++mi) af[mi] = *(const bf16x8*)(as + ((wm * 64 + mi * 32 + r) * 72 + ks * 16 + 8 * h) * 2);
; #pragma unroll
;       for (int ni = 0; ni < 2; ++ni) bfr[ni] = *(const bf16x8*)(bs + ((wn * 64 + ni * 32 + r) * 72 + ks * 16 + 8 * h) * 2);
; #pragma unroll
;       for (int mi = 0; mi < 2; ++mi)
; #pragma unroll
;         for (int ni = 0; ni < 2; ++ni) {
;           if (SWAP) acc[mi][ni] = MFMA32(bfr[ni], af[mi], acc[mi][ni]);
;           else acc[mi][ni] = MFMA32(af[mi], bfr[ni], acc[mi][ni]);
;         }
;     }
;   };
;   gload(0, ra0, rb0);
;   lstore(0, ra0, rb0);
;   gload(1, ra1, rb1);
;   __syncthreads();
;   for (int kt = 0; kt < nk; kt += 2) {
;     if (kt + 2 < nk) gload(kt + 2, ra0, rb0);
;     compute(0);
;     lstore(1, ra1, rb1);
;     __syncthreads();
;     if (kt + 3 < nk) gload(kt + 3, ra1, rb1);
;     compute(1);
;     if (kt + 2 < nk) lstore(0, ra0, rb0);
;     __syncthreads();
	ds_read_b128 v[132:135], v210 offset:0
	ds_read_b128 v[136:139], v210 offset:4096
	ds_read_b128 v[140:143], v214 offset:0
	ds_read_b128 v[144:147], v214 offset:4096
	ds_read_b128 v[148:151], v214 offset:16384
	ds_read_b128 v[158:161], v214 offset:20480
	s_mov_b32 m0, s45
	s_nop 0
	global_load_lds_dwordx4 v208, s[68:69]
	global_load_lds_dwordx4 v209, s[70:71] offset:1024
	global_load_lds_dwordx4 v208, s[72:73] offset:2048
	global_load_lds_dwordx4 v209, s[74:75] offset:3072
	ds_read_b128 v[162:165], v211 offset:0
	ds_read_b128 v[168:171], v211 offset:4096
	ds_read_b128 v[172:175], v215 offset:0
	ds_read_b128 v[176:179], v215 offset:4096
	ds_read_b128 v[180:183], v215 offset:16384
	ds_read_b128 v[184:187], v215 offset:20480
	s_waitcnt lgkmcnt(6)
	v_mfma_f32_32x32x16_bf16 v[4:19], v[140:143], v[132:135], v[4:19]
	v_mfma_f32_32x32x16_bf16 v[68:83], v[140:143], v[136:139], v[68:83]
	v_mfma_f32_32x32x16_bf16 v[20:35], v[144:147], v[132:135], v[20:35]
	v_mfma_f32_32x32x16_bf16 v[84:99], v[144:147], v[136:139], v[84:99]
	v_mfma_f32_32x32x16_bf16 v[36:51], v[148:151], v[132:135], v[36:51]
	v_mfma_f32_32x32x16_bf16 v[100:115], v[148:151], v[136:139], v[100:115]
	v_mfma_f32_32x32x16_bf16 v[52:67], v[158:161], v[132:135], v[52:67]
	v_mfma_f32_32x32x16_bf16 v[116:131], v[158:161], v[136:139], v[116:131]
	s_mov_b32 m0, s47
	s_nop 0
	global_load_lds_dwordx4 v208, s[76:77]
	global_load_lds_dwordx4 v209, s[78:79] offset:1024
	global_load_lds_dwordx4 v208, s[80:81] offset:2048
	global_load_lds_dwordx4 v209, s[82:83] offset:3072
	v_add_u32_e32 v208, 0x80, v208
	v_add_u32_e32 v209, 0x80, v209
	ds_read_b128 v[132:135], v212 offset:0
	ds_read_b128 v[136:139], v212 offset:4096
	ds_read_b128 v[140:143], v216 offset:0
	ds_read_b128 v[144:147], v216 offset:4096
	ds_read_b128 v[148:151], v216 offset:16384
	ds_read_b128 v[158:161], v216 offset:20480
	s_waitcnt lgkmcnt(6)
	v_mfma_f32_32x32x16_bf16 v[4:19], v[172:175], v[162:165], v[4:19]
	v_mfma_f32_32x32x16_bf16 v[68:83], v[172:175], v[168:171], v[68:83]
	v_mfma_f32_32x32x16_bf16 v[20:35], v[176:179], v[162:165], v[20:35]
	v_mfma_f32_32x32x16_bf16 v[84:99], v[176:179], v[168:171], v[84:99]
	v_mfma_f32_32x32x16_bf16 v[36:51], v[180:183], v[162:165], v[36:51]
	v_mfma_f32_32x32x16_bf16 v[100:115], v[180:183], v[168:171], v[100:115]
	v_mfma_f32_32x32x16_bf16 v[52:67], v[184:187], v[162:165], v[52:67]
	v_mfma_f32_32x32x16_bf16 v[116:131], v[184:187], v[168:171], v[116:131]
	ds_read_b128 v[162:165], v213 offset:0
	ds_read_b128 v[168:171], v213 offset:4096
	ds_read_b128 v[172:175], v217 offset:0
	ds_read_b128 v[176:179], v217 offset:4096
	ds_read_b128 v[180:183], v217 offset:16384
	ds_read_b128 v[184:187], v217 offset:20480
	s_waitcnt lgkmcnt(6)
	v_mfma_f32_32x32x16_bf16 v[4:19], v[140:143], v[132:135], v[4:19]
	v_mfma_f32_32x32x16_bf16 v[68:83], v[140:143], v[136:139], v[68:83]
	v_mfma_f32_32x32x16_bf16 v[20:35], v[144:147], v[132:135], v[20:35]
	v_mfma_f32_32x32x16_bf16 v[84:99], v[144:147], v[136:139], v[84:99]
	v_mfma_f32_32x32x16_bf16 v[36:51], v[148:151], v[132:135], v[36:51]
	v_mfma_f32_32x32x16_bf16 v[100:115], v[148:151], v[136:139], v[100:115]
	v_mfma_f32_32x32x16_bf16 v[52:67], v[158:161], v[132:135], v[52:67]
	v_mfma_f32_32x32x16_bf16 v[116:131], v[158:161], v[136:139], v[116:131]
	s_waitcnt lgkmcnt(0)
	v_mfma_f32_32x32x16_bf16 v[4:19], v[172:175], v[162:165], v[4:19]
	v_mfma_f32_32x32x16_bf16 v[68:83], v[172:175], v[168:171], v[68:83]
	v_mfma_f32_32x32x16_bf16 v[20:35], v[176:179], v[162:165], v[20:35]
	v_mfma_f32_32x32x16_bf16 v[84:99], v[176:179], v[168:171], v[84:99]
	v_mfma_f32_32x32x16_bf16 v[36:51], v[180:183], v[162:165], v[36:51]
	v_mfma_f32_32x32x16_bf16 v[100:115], v[180:183], v[168:171], v[100:115]
	v_mfma_f32_32x32x16_bf16 v[52:67], v[184:187], v[162:165], v[52:67]
	v_mfma_f32_32x32x16_bf16 v[116:131], v[184:187], v[168:171], v[116:131]
	s_waitcnt vmcnt(0) lgkmcnt(0)
	s_barrier
	ds_read_b128 v[132:135], v210 offset:32768
	ds_read_b128 v[136:139], v210 offset:36864
	ds_read_b128 v[140:143], v214 offset:32768
	ds_read_b128 v[144:147], v214 offset:36864
	ds_read_b128 v[148:151], v214 offset:49152
	ds_read_b128 v[158:161], v214 offset:53248
	s_mov_b32 m0, s44
	s_nop 0
	global_load_lds_dwordx4 v208, s[68:69]
	global_load_lds_dwordx4 v209, s[70:71] offset:1024
	global_load_lds_dwordx4 v208, s[72:73] offset:2048
	global_load_lds_dwordx4 v209, s[74:75] offset:3072
	ds_read_b128 v[162:165], v211 offset:32768
	ds_read_b128 v[168:171], v211 offset:36864
	ds_read_b128 v[172:175], v215 offset:32768
	ds_read_b128 v[176:179], v215 offset:36864
	ds_read_b128 v[180:183], v215 offset:49152
	ds_read_b128 v[184:187], v215 offset:53248
	s_waitcnt lgkmcnt(6)
	v_mfma_f32_32x32x16_bf16 v[4:19], v[140:143], v[132:135], v[4:19]
	v_mfma_f32_32x32x16_bf16 v[68:83], v[140:143], v[136:139], v[68:83]
	v_mfma_f32_32x32x16_bf16 v[20:35], v[144:147], v[132:135], v[20:35]
	v_mfma_f32_32x32x16_bf16 v[84:99], v[144:147], v[136:139], v[84:99]
	v_mfma_f32_32x32x16_bf16 v[36:51], v[148:151], v[132:135], v[36:51]
	v_mfma_f32_32x32x16_bf16 v[100:115], v[148:151], v[136:139], v[100:115]
	v_mfma_f32_32x32x16_bf16 v[52:67], v[158:161], v[132:135], v[52:67]
	v_mfma_f32_32x32x16_bf16 v[116:131], v[158:161], v[136:139], v[116:131]
	s_mov_b32 m0, s46
	s_nop 0
	global_load_lds_dwordx4 v208, s[76:77]
	global_load_lds_dwordx4 v209, s[78:79] offset:1024
	global_load_lds_dwordx4 v208, s[80:81] offset:2048
	global_load_lds_dwordx4 v209, s[82:83] offset:3072
	v_add_u32_e32 v208, 0x80, v208
	v_add_u32_e32 v209, 0x80, v209
	ds_read_b128 v[132:135], v212 offset:32768
	ds_read_b128 v[136:139], v212 offset:36864
	ds_read_b128 v[140:143], v216 offset:32768
	ds_read_b128 v[144:147], v216 offset:36864
	ds_read_b128 v[148:151], v216 offset:49152
	ds_read_b128 v[158:161], v216 offset:53248
	s_waitcnt lgkmcnt(6)
; #define MFMA32(a, b, c) __builtin_amdgcn_mfma_f32_32x32x16_bf16((a), (b), (c), 0, 0, 0)
; template <bool SWAP, class Epi>
; DI void gemm_tile(const u16* __restrict__ A, int lda, const u16* __restrict__ Bw, int ldb, int K, char* lds, Epi epi) {
;     ...
;   auto compute = [&](int st) {
;     const char* as = lds + st * GEMM_STAGE;
;     const char* bs = as + 36864;
; #pragma unroll
;     for (int ks = 0; ks < 4; ++ks) {
;       bf16x8 af[2], bfr[2];
; #pragma unroll
;       for (int mi = 0; mi < 2; ++mi) af[mi] = *(const bf16x8*)(as + ((wm * 64 + mi * 32 + r) * 72 + ks * 16 + 8 * h) * 2);
; #pragma unroll
;       for (int ni = 0; ni < 2; ++ni) bfr[ni] = *(const bf16x8*)(bs + ((wn * 64 + ni * 32 + r) * 72 + ks * 16 + 8 * h) * 2);
; #pragma unroll
;       for (int mi = 0; mi < 2; ++mi)
; #pragma unroll
;         for (int ni = 0; ni < 2; ++ni) {
;           if (SWAP) acc[mi][ni] = MFMA32(bfr[ni], af[mi], acc[mi][ni]);
;           else acc[mi][ni] = MFMA32(af[mi], bfr[ni], acc[mi][ni]);
;         }
;     }
;   };
;   gload(0, ra0, rb0);
;   lstore(0, ra0, rb0);
;   gload(1, ra1, rb1);
;   __syncthreads();
;   for (int kt = 0; kt < nk; kt += 2) {
;     if (kt + 2 < nk) gload(kt + 2, ra0, rb0);
;     compute(0);
;     lstore(1, ra1, rb1);
;     __syncthreads();
;     if (kt + 3 < nk) gload(kt + 3, ra1, rb1);
;     compute(1);
;     if (kt + 2 < nk) lstore(0, ra0, rb0);
;     __syncthreads();
	v_mfma_f32_32x32x16_bf16 v[4:19], v[172:175], v[162:165], v[4:19]
	v_mfma_f32_32x32x16_bf16 v[68:83], v[172:175], v[168:171], v[68:83]
	v_mfma_f32_32x32x16_bf16 v[20:35], v[176:179], v[162:165], v[20:35]
	v_mfma_f32_32x32x16_bf16 v[84:99], v[176:179], v[168:171], v[84:99]
	v_mfma_f32_32x32x16_bf16 v[36:51], v[180:183], v[162:165], v[36:51]
	v_mfma_f32_32x32x16_bf16 v[100:115], v[180:183], v[168:171], v[100:115]
	v_mfma_f32_32x32x16_bf16 v[52:67], v[184:187], v[162:165], v[52:67]
	v_mfma_f32_32x32x16_bf16 v[116:131], v[184:187], v[168:171], v[116:131]
	ds_read_b128 v[162:165], v213 offset:32768
	ds_read_b128 v[168:171], v213 offset:36864
	ds_read_b128 v[172:175], v217 offset:32768
	ds_read_b128 v[176:179], v217 offset:36864
	ds_read_b128 v[180:183], v217 offset:49152
	ds_read_b128 v[184:187], v217 offset:53248
	s_waitcnt lgkmcnt(6)
	v_mfma_f32_32x32x16_bf16 v[4:19], v[140:143], v[132:135], v[4:19]
	v_mfma_f32_32x32x16_bf16 v[68:83], v[140:143], v[136:139], v[68:83]
	v_mfma_f32_32x32x16_bf16 v[20:35], v[144:147], v[132:135], v[20:35]
	v_mfma_f32_32x32x16_bf16 v[84:99], v[144:147], v[136:139], v[84:99]
	v_mfma_f32_32x32x16_bf16 v[36:51], v[148:151], v[132:135], v[36:51]
	v_mfma_f32_32x32x16_bf16 v[100:115], v[148:151], v[136:139], v[100:115]
	v_mfma_f32_32x32x16_bf16 v[52:67], v[158:161], v[132:135], v[52:67]
	v_mfma_f32_32x32x16_bf16 v[116:131], v[158:161], v[136:139], v[116:131]
	s_waitcnt lgkmcnt(0)
	v_mfma_f32_32x32x16_bf16 v[4:19], v[172:175], v[162:165], v[4:19]
	v_mfma_f32_32x32x16_bf16 v[68:83], v[172:175], v[168:171], v[68:83]
	v_mfma_f32_32x32x16_bf16 v[20:35], v[176:179], v[162:165], v[20:35]
	v_mfma_f32_32x32x16_bf16 v[84:99], v[176:179], v[168:171], v[84:99]
	v_mfma_f32_32x32x16_bf16 v[36:51], v[180:183], v[162:165], v[36:51]
	v_mfma_f32_32x32x16_bf16 v[100:115], v[180:183], v[168:171], v[100:115]
	v_mfma_f32_32x32x16_bf16 v[52:67], v[184:187], v[162:165], v[52:67]
	v_mfma_f32_32x32x16_bf16 v[116:131], v[184:187], v[168:171], v[116:131]
	s_waitcnt vmcnt(0) lgkmcnt(0)
	s_barrier
	ds_read_b128 v[132:135], v210 offset:0
	ds_read_b128 v[136:139], v210 offset:4096
	ds_read_b128 v[140:143], v214 offset:0
	ds_read_b128 v[144:147], v214 offset:4096
	ds_read_b128 v[148:151], v214 offset:16384
	ds_read_b128 v[158:161], v214 offset:20480
	s_mov_b32 m0, s45
	s_nop 0
	global_load_lds_dwordx4 v208, s[68:69]
	global_load_lds_dwordx4 v209, s[70:71] offset:1024
	global_load_lds_dwordx4 v208, s[72:73] offset:2048
	global_load_lds_dwordx4 v209, s[74:75] offset:3072
	ds_read_b128 v[162:165], v211 offset:0
	ds_read_b128 v[168:171], v211 offset:4096
	ds_read_b128 v[172:175], v215 offset:0
	ds_read_b128 v[176:179], v215 offset:4096
	ds_read_b128 v[180:183], v215 offset:16384
	ds_read_b128 v[184:187], v215 offset:20480
	s_waitcnt lgkmcnt(6)
	v_mfma_f32_32x32x16_bf16 v[4:19], v[140:143], v[132:135], v[4:19]
	v_mfma_f32_32x32x16_bf16 v[68:83], v[140:143], v[136:139], v[68:83]
	v_mfma_f32_32x32x16_bf16 v[20:35], v[144:147], v[132:135], v[20:35]
	v_mfma_f32_32x32x16_bf16 v[84:99], v[144:147], v[136:139], v[84:99]
	v_mfma_f32_32x32x16_bf16 v[36:51], v[148:151], v[132:135], v[36:51]
	v_mfma_f32_32x32x16_bf16 v[100:115], v[148:151], v[136:139], v[100:115]
	v_mfma_f32_32x32x16_bf16 v[52:67], v[158:161], v[132:135], v[52:67]
	v_mfma_f32_32x32x16_bf16 v[116:131], v[158:161], v[136:139], v[116:131]
	s_mov_b32 m0, s47
	s_nop 0
	global_load_lds_dwordx4 v208, s[76:77]
	global_load_lds_dwordx4 v209, s[78:79] offset:1024
	global_load_lds_dwordx4 v208, s[80:81] offset:2048
	global_load_lds_dwordx4 v209, s[82:83] offset:3072
	v_add_u32_e32 v208, 0x80, v208
	v_add_u32_e32 v209, 0x80, v209
	ds_read_b128 v[132:135], v212 offset:0
	ds_read_b128 v[136:139], v212 offset:4096
	ds_read_b128 v[140:143], v216 offset:0
	ds_read_b128 v[144:147], v216 offset:4096
	ds_read_b128 v[148:151], v216 offset:16384
	ds_read_b128 v[158:161], v216 offset:20480
	s_waitcnt lgkmcnt(6)
	v_mfma_f32_32x32x16_bf16 v[4:19], v[172:175], v[162:165], v[4:19]
	v_mfma_f32_32x32x16_bf16 v[68:83], v[172:175], v[168:171], v[68:83]
	v_mfma_f32_32x32x16_bf16 v[20:35], v[176:179], v[162:165], v[20:35]
	v_mfma_f32_32x32x16_bf16 v[84:99], v[176:179], v[168:171], v[84:99]
	v_mfma_f32_32x32x16_bf16 v[36:51], v[180:183], v[162:165], v[36:51]
	v_mfma_f32_32x32x16_bf16 v[100:115], v[180:183], v[168:171], v[100:115]
	v_mfma_f32_32x32x16_bf16 v[52:67], v[184:187], v[162:165], v[52:67]
	v_mfma_f32_32x32x16_bf16 v[116:131], v[184:187], v[168:171], v[116:131]
	ds_read_b128 v[162:165], v213 offset:0
	ds_read_b128 v[168:171], v213 offset:4096
	ds_read_b128 v[172:175], v217 offset:0
	ds_read_b128 v[176:179], v217 offset:4096
	ds_read_b128 v[180:183], v217 offset:16384
	ds_read_b128 v[184:187], v217 offset:20480
	s_waitcnt lgkmcnt(6)
	v_mfma_f32_32x32x16_bf16 v[4:19], v[140:143], v[132:135], v[4:19]
	v_mfma_f32_32x32x16_bf16 v[68:83], v[140:143], v[136:139], v[68:83]
	v_mfma_f32_32x32x16_bf16 v[20:35], v[144:147], v[132:135], v[20:35]
	v_mfma_f32_32x32x16_bf16 v[84:99], v[144:147], v[136:139], v[84:99]
	v_mfma_f32_32x32x16_bf16 v[36:51], v[148:151], v[132:135], v[36:51]
	v_mfma_f32_32x32x16_bf16 v[100:115], v[148:151], v[136:139], v[100:115]
	v_mfma_f32_32x32x16_bf16 v[52:67], v[158:161], v[132:135], v[52:67]
	v_mfma_f32_32x32x16_bf16 v[116:131], v[158:161], v[136:139], v[116:131]
	s_waitcnt lgkmcnt(0)
	v_mfma_f32_32x32x16_bf16 v[4:19], v[172:175], v[162:165], v[4:19]
	v_mfma_f32_32x32x16_bf16 v[68:83], v[172:175], v[168:171], v[68:83]
	v_mfma_f32_32x32x16_bf16 v[20:35], v[176:179], v[162:165], v[20:35]
	v_mfma_f32_32x32x16_bf16 v[84:99], v[176:179], v[168:171], v[84:99]
	v_mfma_f32_32x32x16_bf16 v[36:51], v[180:183], v[162:165], v[36:51]
	v_mfma_f32_32x32x16_bf16 v[100:115], v[180:183], v[168:171], v[100:115]
	v_mfma_f32_32x32x16_bf16 v[52:67], v[184:187], v[162:165], v[52:67]
	v_mfma_f32_32x32x16_bf16 v[116:131], v[184:187], v[168:171], v[116:131]
	s_waitcnt vmcnt(0) lgkmcnt(0)
	s_barrier
; #define MFMA32(a, b, c) __builtin_amdgcn_mfma_f32_32x32x16_bf16((a), (b), (c), 0, 0, 0)
; DI unsigned pk2(float a, float b) { f32x2 v = {a, b}; return __builtin_bit_cast(unsigned, __builtin_convertvector(v, bf2_t)); }
; template <bool SWAP, class Epi>
; DI void gemm_tile(const u16* __restrict__ A, int lda, const u16* __restrict__ Bw, int ldb, int K, char* lds, Epi epi) {
;     ...
;   auto compute = [&](int st) {
;     const char* as = lds + st * GEMM_STAGE;
;     const char* bs = as + 36864;
; #pragma unroll
;     for (int ks = 0; ks < 4; ++ks) {
;       bf16x8 af[2], bfr[2];
; #pragma unroll
;       for (int mi = 0; mi < 2; ++mi) af[mi] = *(const bf16x8*)(as + ((wm * 64 + mi * 32 + r) * 72 + ks * 16 + 8 * h) * 2);
; #pragma unroll
;       for (int ni = 0; ni < 2; ++ni) bfr[ni] = *(const bf16x8*)(bs + ((wn * 64 + ni * 32 + r) * 72 + ks * 16 + 8 * h) * 2);
; #pragma unroll
;       for (int mi = 0; mi < 2; ++mi)
; #pragma unroll
;         for (int ni = 0; ni < 2; ++ni) {
;           if (SWAP) acc[mi][ni] = MFMA32(bfr[ni], af[mi], acc[mi][ni]);
;           else acc[mi][ni] = MFMA32(af[mi], bfr[ni], acc[mi][ni]);
;         }
;     }
;   };
;   gload(0, ra0, rb0);
;   lstore(0, ra0, rb0);
;   gload(1, ra1, rb1);
;   __syncthreads();
;   for (int kt = 0; kt < nk; kt += 2) {
;     if (kt + 2 < nk) gload(kt + 2, ra0, rb0);
;     compute(0);
;     lstore(1, ra1, rb1);
;     __syncthreads();
;     if (kt + 3 < nk) gload(kt + 3, ra1, rb1);
;     compute(1);
;     if (kt + 2 < nk) lstore(0, ra0, rb0);
;     __syncthreads();
; DI void store_rowmajor(u16* dst, const f32x16& a, int h, float sc) {
; #pragma unroll
;   for (int kp = 0; kp < 2; ++kp) {
;     const int g = 2 * kp;
;     unsigned ax = pk2(a[4 * g] * sc, a[4 * g + 1] * sc), ay = pk2(a[4 * g + 2] * sc, a[4 * g + 3] * sc);
;     unsigned bx = pk2(a[4 * g + 4] * sc, a[4 * g + 5] * sc), by = pk2(a[4 * g + 6] * sc, a[4 * g + 7] * sc);
;     const u32x2 rx = __builtin_amdgcn_permlane32_swap(ax, bx, false, false);
;     const u32x2 ry = __builtin_amdgcn_permlane32_swap(ay, by, false, false);
;     const u32x4 v = {rx[0], ry[0], rx[1], ry[1]};
;     *(u32x4*)(dst + 8 * (g + h)) = v;
;   }
; }
	ds_read_b128 v[132:135], v210 offset:32768
	ds_read_b128 v[136:139], v210 offset:36864
	ds_read_b128 v[140:143], v214 offset:32768
	ds_read_b128 v[144:147], v214 offset:36864
	ds_read_b128 v[148:151], v214 offset:49152
	ds_read_b128 v[158:161], v214 offset:53248
	ds_read_b128 v[162:165], v211 offset:32768
	ds_read_b128 v[168:171], v211 offset:36864
	ds_read_b128 v[172:175], v215 offset:32768
	ds_read_b128 v[176:179], v215 offset:36864
	ds_read_b128 v[180:183], v215 offset:49152
	ds_read_b128 v[184:187], v215 offset:53248
	s_waitcnt lgkmcnt(6)
	v_mfma_f32_32x32x16_bf16 v[4:19], v[140:143], v[132:135], v[4:19]
	v_mfma_f32_32x32x16_bf16 v[68:83], v[140:143], v[136:139], v[68:83]
	v_mfma_f32_32x32x16_bf16 v[20:35], v[144:147], v[132:135], v[20:35]
	v_mfma_f32_32x32x16_bf16 v[84:99], v[144:147], v[136:139], v[84:99]
	v_mfma_f32_32x32x16_bf16 v[36:51], v[148:151], v[132:135], v[36:51]
	v_mfma_f32_32x32x16_bf16 v[100:115], v[148:151], v[136:139], v[100:115]
	v_mfma_f32_32x32x16_bf16 v[52:67], v[158:161], v[132:135], v[52:67]
	v_mfma_f32_32x32x16_bf16 v[116:131], v[158:161], v[136:139], v[116:131]
	ds_read_b128 v[132:135], v212 offset:32768
	ds_read_b128 v[136:139], v212 offset:36864
	ds_read_b128 v[140:143], v216 offset:32768
	ds_read_b128 v[144:147], v216 offset:36864
	ds_read_b128 v[148:151], v216 offset:49152
	ds_read_b128 v[158:161], v216 offset:53248
	s_waitcnt lgkmcnt(6)
	v_mfma_f32_32x32x16_bf16 v[4:19], v[172:175], v[162:165], v[4:19]
	v_mfma_f32_32x32x16_bf16 v[68:83], v[172:175], v[168:171], v[68:83]
	v_mfma_f32_32x32x16_bf16 v[20:35], v[176:179], v[162:165], v[20:35]
	v_mfma_f32_32x32x16_bf16 v[84:99], v[176:179], v[168:171], v[84:99]
	v_mfma_f32_32x32x16_bf16 v[36:51], v[180:183], v[162:165], v[36:51]
	v_mfma_f32_32x32x16_bf16 v[100:115], v[180:183], v[168:171], v[100:115]
	v_mfma_f32_32x32x16_bf16 v[52:67], v[184:187], v[162:165], v[52:67]
	v_mfma_f32_32x32x16_bf16 v[116:131], v[184:187], v[168:171], v[116:131]
	ds_read_b128 v[162:165], v213 offset:32768
	ds_read_b128 v[168:171], v213 offset:36864
	ds_read_b128 v[172:175], v217 offset:32768
	ds_read_b128 v[176:179], v217 offset:36864
	ds_read_b128 v[180:183], v217 offset:49152
	ds_read_b128 v[184:187], v217 offset:53248
	s_waitcnt lgkmcnt(6)
	v_mfma_f32_32x32x16_bf16 v[4:19], v[140:143], v[132:135], v[4:19]
	v_mfma_f32_32x32x16_bf16 v[68:83], v[140:143], v[136:139], v[68:83]
	v_mfma_f32_32x32x16_bf16 v[20:35], v[144:147], v[132:135], v[20:35]
	v_mfma_f32_32x32x16_bf16 v[84:99], v[144:147], v[136:139], v[84:99]
	v_mfma_f32_32x32x16_bf16 v[36:51], v[148:151], v[132:135], v[36:51]
	v_mfma_f32_32x32x16_bf16 v[100:115], v[148:151], v[136:139], v[100:115]
	v_mfma_f32_32x32x16_bf16 v[52:67], v[158:161], v[132:135], v[52:67]
	v_mfma_f32_32x32x16_bf16 v[116:131], v[158:161], v[136:139], v[116:131]
	s_waitcnt lgkmcnt(0)
	v_mfma_f32_32x32x16_bf16 v[4:19], v[172:175], v[162:165], v[4:19]
	v_mfma_f32_32x32x16_bf16 v[68:83], v[172:175], v[168:171], v[68:83]
	v_mfma_f32_32x32x16_bf16 v[20:35], v[176:179], v[162:165], v[20:35]
	v_mfma_f32_32x32x16_bf16 v[84:99], v[176:179], v[168:171], v[84:99]
	v_mfma_f32_32x32x16_bf16 v[36:51], v[180:183], v[162:165], v[36:51]
	v_mfma_f32_32x32x16_bf16 v[100:115], v[180:183], v[168:171], v[100:115]
	v_mfma_f32_32x32x16_bf16 v[52:67], v[184:187], v[162:165], v[52:67]
	v_mfma_f32_32x32x16_bf16 v[116:131], v[184:187], v[168:171], v[116:131]
	s_waitcnt lgkmcnt(0)
	s_barrier
	s_addk_i32 s101, 0x20
	s_cmpk_ge_u32 s101, 0xd1
	s_cbranch_scc1 .Lpp_last
	s_mul_i32 s0, s101, 0x5556
	s_lshr_b32 s26, s0, 16
	s_mul_i32 s0, s26, 3
	s_sub_i32 s0, s101, s0
	s_mul_i32 s0, s0, 6
	s_add_i32 s0, s0, s41
	s_cmpk_lt_u32 s101, 0xc6
	s_cbranch_scc1 .Lpp_col2
	s_mul_i32 s1, s41, 11
	s_add_i32 s1, s1, s101
	s_sub_i32 s26, s1, 0xc6
	s_movk_i32 s0, 18
.Lpp_col2:
	s_lshl_b32 s1, s0, 1
	s_cmp_gt_u32 s0, 1
	s_cselect_b32 s2, 4, 0
	s_add_i32 s2, s1, s2
	v_readlane_b32 s4, v241, 26
	v_readlane_b32 s5, v241, 27
	s_lshl_b32 s0, s26, 19
	s_add_u32 s4, s4, s0
	s_addc_u32 s5, s5, 0
	s_lshl_b32 s0, s2, 18
	s_add_u32 s6, s18, s0
	s_addc_u32 s7, s19, 0
	s_add_u32 s68, s4, s13
	s_addc_u32 s69, s5, 0
	s_add_u32 s70, s68, 0x3c00
	s_addc_u32 s71, s69, 0
	s_add_u32 s72, s70, 0x3c00
	s_addc_u32 s73, s71, 0
	s_add_u32 s74, s72, 0x3c00
	s_addc_u32 s75, s73, 0
	s_add_u32 s76, s6, s13
	s_addc_u32 s77, s7, 0
	s_add_u32 s78, s76, 0x3c00
	s_addc_u32 s79, s77, 0
	s_add_u32 s80, s78, 0x3c00
	s_addc_u32 s81, s79, 0
	s_add_u32 s82, s80, 0x3c00
	s_addc_u32 s83, s81, 0
	v_mov_b32_e32 v208, v232
	v_mov_b32_e32 v209, v233
	s_mov_b32 m0, s44
	s_nop 0
	global_load_lds_dwordx4 v208, s[68:69]
	global_load_lds_dwordx4 v209, s[70:71] offset:1024
	global_load_lds_dwordx4 v208, s[72:73] offset:2048
	global_load_lds_dwordx4 v209, s[74:75] offset:3072
	s_mov_b32 m0, s46
	s_nop 0
	global_load_lds_dwordx4 v208, s[76:77]
	global_load_lds_dwordx4 v209, s[78:79] offset:1024
	global_load_lds_dwordx4 v208, s[80:81] offset:2048
	global_load_lds_dwordx4 v209, s[82:83] offset:3072
	v_add_u32_e32 v208, 0x80, v208
	v_add_u32_e32 v209, 0x80, v209
	s_nop 7
	s_nop 7
	v_cvt_pk_bf16_f32 v224, v4, v5
	v_cvt_pk_bf16_f32 v225, v6, v7
	v_cvt_pk_bf16_f32 v226, v8, v9
	v_cvt_pk_bf16_f32 v227, v10, v11
	s_nop 1
	v_permlane32_swap_b32_e32 v224, v226
	v_permlane32_swap_b32_e32 v225, v227
	s_nop 0
	global_store_dwordx4 v218, v[224:227], s[8:9]
	v_cvt_pk_bf16_f32 v228, v12, v13
	v_cvt_pk_bf16_f32 v229, v14, v15
	v_cvt_pk_bf16_f32 v230, v16, v17
	v_cvt_pk_bf16_f32 v231, v18, v19
	s_nop 1
	v_permlane32_swap_b32_e32 v228, v230
	v_permlane32_swap_b32_e32 v229, v231
	s_nop 0
	global_store_dwordx4 v218, v[228:231], s[8:9] offset:32
	v_cvt_pk_bf16_f32 v224, v68, v69
; DI unsigned pk2(float a, float b) { f32x2 v = {a, b}; return __builtin_bit_cast(unsigned, __builtin_convertvector(v, bf2_t)); }
; DI void store_rowmajor(u16* dst, const f32x16& a, int h, float sc) {
; #pragma unroll
;   for (int kp = 0; kp < 2; ++kp) {
;     const int g = 2 * kp;
;     unsigned ax = pk2(a[4 * g] * sc, a[4 * g + 1] * sc), ay = pk2(a[4 * g + 2] * sc, a[4 * g + 3] * sc);
;     unsigned bx = pk2(a[4 * g + 4] * sc, a[4 * g + 5] * sc), by = pk2(a[4 * g + 6] * sc, a[4 * g + 7] * sc);
;     const u32x2 rx = __builtin_amdgcn_permlane32_swap(ax, bx, false, false);
;     const u32x2 ry = __builtin_amdgcn_permlane32_swap(ay, by, false, false);
;     const u32x4 v = {rx[0], ry[0], rx[1], ry[1]};
;     *(u32x4*)(dst + 8 * (g + h)) = v;
;   }
; }
	v_cvt_pk_bf16_f32 v225, v70, v71
	v_cvt_pk_bf16_f32 v226, v72, v73
	v_cvt_pk_bf16_f32 v227, v74, v75
	s_nop 1
	v_permlane32_swap_b32_e32 v224, v226
	v_permlane32_swap_b32_e32 v225, v227
	s_nop 0
	global_store_dwordx4 v219, v[224:227], s[8:9]
	v_cvt_pk_bf16_f32 v228, v76, v77
	v_cvt_pk_bf16_f32 v229, v78, v79
	v_cvt_pk_bf16_f32 v230, v80, v81
	v_cvt_pk_bf16_f32 v231, v82, v83
	s_nop 1
	v_permlane32_swap_b32_e32 v228, v230
	v_permlane32_swap_b32_e32 v229, v231
	s_nop 0
	global_store_dwordx4 v219, v[228:231], s[8:9] offset:32
	v_cvt_pk_bf16_f32 v224, v20, v21
	v_cvt_pk_bf16_f32 v225, v22, v23
	v_cvt_pk_bf16_f32 v226, v24, v25
	v_cvt_pk_bf16_f32 v227, v26, v27
	s_nop 1
	v_permlane32_swap_b32_e32 v224, v226
	v_permlane32_swap_b32_e32 v225, v227
	s_nop 0
	global_store_dwordx4 v218, v[224:227], s[8:9] offset:64
	v_cvt_pk_bf16_f32 v228, v28, v29
	v_cvt_pk_bf16_f32 v229, v30, v31
	v_cvt_pk_bf16_f32 v230, v32, v33
	v_cvt_pk_bf16_f32 v231, v34, v35
	s_nop 1
	v_permlane32_swap_b32_e32 v228, v230
	v_permlane32_swap_b32_e32 v229, v231
	s_nop 0
	global_store_dwordx4 v218, v[228:231], s[8:9] offset:96
	v_cvt_pk_bf16_f32 v224, v84, v85
	v_cvt_pk_bf16_f32 v225, v86, v87
	v_cvt_pk_bf16_f32 v226, v88, v89
	v_cvt_pk_bf16_f32 v227, v90, v91
	s_nop 1
	v_permlane32_swap_b32_e32 v224, v226
	v_permlane32_swap_b32_e32 v225, v227
	s_nop 0
	global_store_dwordx4 v219, v[224:227], s[8:9] offset:64
	v_cvt_pk_bf16_f32 v228, v92, v93
	v_cvt_pk_bf16_f32 v229, v94, v95
	v_cvt_pk_bf16_f32 v230, v96, v97
	v_cvt_pk_bf16_f32 v231, v98, v99
	s_nop 1
	v_permlane32_swap_b32_e32 v228, v230
	v_permlane32_swap_b32_e32 v229, v231
	s_nop 0
	global_store_dwordx4 v219, v[228:231], s[8:9] offset:96
	v_cvt_pk_bf16_f32 v224, v36, v37
	v_cvt_pk_bf16_f32 v225, v38, v39
	v_cvt_pk_bf16_f32 v226, v40, v41
	v_cvt_pk_bf16_f32 v227, v42, v43
	s_nop 1
	v_permlane32_swap_b32_e32 v224, v226
	v_permlane32_swap_b32_e32 v225, v227
	s_nop 0
	global_store_dwordx4 v218, v[224:227], s[8:9] offset:256
	v_cvt_pk_bf16_f32 v228, v44, v45
	v_cvt_pk_bf16_f32 v229, v46, v47
	v_cvt_pk_bf16_f32 v230, v48, v49
	v_cvt_pk_bf16_f32 v231, v50, v51
	s_nop 1
	v_permlane32_swap_b32_e32 v228, v230
	v_permlane32_swap_b32_e32 v229, v231
	s_nop 0
	global_store_dwordx4 v218, v[228:231], s[8:9] offset:288
	v_cvt_pk_bf16_f32 v224, v100, v101
	v_cvt_pk_bf16_f32 v225, v102, v103
	v_cvt_pk_bf16_f32 v226, v104, v105
	v_cvt_pk_bf16_f32 v227, v106, v107
	s_nop 1
	v_permlane32_swap_b32_e32 v224, v226
	v_permlane32_swap_b32_e32 v225, v227
	s_nop 0
	global_store_dwordx4 v219, v[224:227], s[8:9] offset:256
	v_cvt_pk_bf16_f32 v228, v108, v109
	v_cvt_pk_bf16_f32 v229, v110, v111
	v_cvt_pk_bf16_f32 v230, v112, v113
	v_cvt_pk_bf16_f32 v231, v114, v115
	s_nop 1
	v_permlane32_swap_b32_e32 v228, v230
	v_permlane32_swap_b32_e32 v229, v231
	s_nop 0
	global_store_dwordx4 v219, v[228:231], s[8:9] offset:288
	v_cvt_pk_bf16_f32 v224, v52, v53
	v_cvt_pk_bf16_f32 v225, v54, v55
	v_cvt_pk_bf16_f32 v226, v56, v57
	v_cvt_pk_bf16_f32 v227, v58, v59
	s_nop 1
	v_permlane32_swap_b32_e32 v224, v226
	v_permlane32_swap_b32_e32 v225, v227
	s_nop 0
	global_store_dwordx4 v218, v[224:227], s[8:9] offset:320
	v_cvt_pk_bf16_f32 v228, v60, v61
	v_cvt_pk_bf16_f32 v229, v62, v63
	v_cvt_pk_bf16_f32 v230, v64, v65
	v_cvt_pk_bf16_f32 v231, v66, v67
	s_nop 1
	v_permlane32_swap_b32_e32 v228, v230
	v_permlane32_swap_b32_e32 v229, v231
	s_nop 0
	global_store_dwordx4 v218, v[228:231], s[8:9] offset:352
	v_cvt_pk_bf16_f32 v224, v116, v117
	v_cvt_pk_bf16_f32 v225, v118, v119
	v_cvt_pk_bf16_f32 v226, v120, v121
	v_cvt_pk_bf16_f32 v227, v122, v123
	s_nop 1
	v_permlane32_swap_b32_e32 v224, v226
	v_permlane32_swap_b32_e32 v225, v227
	s_nop 0
	global_store_dwordx4 v219, v[224:227], s[8:9] offset:320
	v_cvt_pk_bf16_f32 v228, v124, v125
	v_cvt_pk_bf16_f32 v229, v126, v127
	v_cvt_pk_bf16_f32 v230, v128, v129
	v_cvt_pk_bf16_f32 v231, v130, v131
	s_nop 1
	v_permlane32_swap_b32_e32 v228, v230
	v_permlane32_swap_b32_e32 v229, v231
	s_nop 0
	global_store_dwordx4 v219, v[228:231], s[8:9] offset:352
	s_branch .Lpp_loop
; DI unsigned pk2(float a, float b) { f32x2 v = {a, b}; return __builtin_bit_cast(unsigned, __builtin_convertvector(v, bf2_t)); }
; DI void store_rowmajor(u16* dst, const f32x16& a, int h, float sc) {
; #pragma unroll
;   for (int kp = 0; kp < 2; ++kp) {
;     const int g = 2 * kp;
;     unsigned ax = pk2(a[4 * g] * sc, a[4 * g + 1] * sc), ay = pk2(a[4 * g + 2] * sc, a[4 * g + 3] * sc);
;     unsigned bx = pk2(a[4 * g + 4] * sc, a[4 * g + 5] * sc), by = pk2(a[4 * g + 6] * sc, a[4 * g + 7] * sc);
;     const u32x2 rx = __builtin_amdgcn_permlane32_swap(ax, bx, false, false);
;     const u32x2 ry = __builtin_amdgcn_permlane32_swap(ay, by, false, false);
;     const u32x4 v = {rx[0], ry[0], rx[1], ry[1]};
;     *(u32x4*)(dst + 8 * (g + h)) = v;
;   }
; }
; DI void inproj_tile(const Params& p, int l, int mt, int nt, char* lds) {
;     ...
;     gemm_tile<true>(A, DM, Bw, DM, DM, lds, [&](int mi, int ni, const f32x16& a) {
;       const int tok = m0 + wm * 64 + mi * 32 + r;
;       store_rowmajor(p.H + (size_t)tok * LDH + nt * 128 + wn * 64 + ni * 32, a, h, 1.f);
.Lpp_last:
	s_nop 7
	s_nop 7
	v_cvt_pk_bf16_f32 v224, v4, v5
	v_cvt_pk_bf16_f32 v225, v6, v7
	v_cvt_pk_bf16_f32 v226, v8, v9
	v_cvt_pk_bf16_f32 v227, v10, v11
	s_nop 1
	v_permlane32_swap_b32_e32 v224, v226
	v_permlane32_swap_b32_e32 v225, v227
	s_nop 0
	global_store_dwordx4 v218, v[224:227], s[8:9]
	v_cvt_pk_bf16_f32 v228, v12, v13
	v_cvt_pk_bf16_f32 v229, v14, v15
	v_cvt_pk_bf16_f32 v230, v16, v17
	v_cvt_pk_bf16_f32 v231, v18, v19
	s_nop 1
	v_permlane32_swap_b32_e32 v228, v230
	v_permlane32_swap_b32_e32 v229, v231
	s_nop 0
	global_store_dwordx4 v218, v[228:231], s[8:9] offset:32
	v_cvt_pk_bf16_f32 v224, v68, v69
	v_cvt_pk_bf16_f32 v225, v70, v71
	v_cvt_pk_bf16_f32 v226, v72, v73
	v_cvt_pk_bf16_f32 v227, v74, v75
	s_nop 1
	v_permlane32_swap_b32_e32 v224, v226
	v_permlane32_swap_b32_e32 v225, v227
	s_nop 0
	global_store_dwordx4 v219, v[224:227], s[8:9]
	v_cvt_pk_bf16_f32 v228, v76, v77
	v_cvt_pk_bf16_f32 v229, v78, v79
	v_cvt_pk_bf16_f32 v230, v80, v81
	v_cvt_pk_bf16_f32 v231, v82, v83
	s_nop 1
	v_permlane32_swap_b32_e32 v228, v230
	v_permlane32_swap_b32_e32 v229, v231
	s_nop 0
	global_store_dwordx4 v219, v[228:231], s[8:9] offset:32
	v_cvt_pk_bf16_f32 v224, v20, v21
	v_cvt_pk_bf16_f32 v225, v22, v23
	v_cvt_pk_bf16_f32 v226, v24, v25
	v_cvt_pk_bf16_f32 v227, v26, v27
	s_nop 1
	v_permlane32_swap_b32_e32 v224, v226
	v_permlane32_swap_b32_e32 v225, v227
	s_nop 0
	global_store_dwordx4 v218, v[224:227], s[8:9] offset:64
	v_cvt_pk_bf16_f32 v228, v28, v29
	v_cvt_pk_bf16_f32 v229, v30, v31
	v_cvt_pk_bf16_f32 v230, v32, v33
	v_cvt_pk_bf16_f32 v231, v34, v35
	s_nop 1
	v_permlane32_swap_b32_e32 v228, v230
	v_permlane32_swap_b32_e32 v229, v231
	s_nop 0
	global_store_dwordx4 v218, v[228:231], s[8:9] offset:96
	v_cvt_pk_bf16_f32 v224, v84, v85
	v_cvt_pk_bf16_f32 v225, v86, v87
	v_cvt_pk_bf16_f32 v226, v88, v89
	v_cvt_pk_bf16_f32 v227, v90, v91
	s_nop 1
	v_permlane32_swap_b32_e32 v224, v226
	v_permlane32_swap_b32_e32 v225, v227
	s_nop 0
	global_store_dwordx4 v219, v[224:227], s[8:9] offset:64
	v_cvt_pk_bf16_f32 v228, v92, v93
	v_cvt_pk_bf16_f32 v229, v94, v95
	v_cvt_pk_bf16_f32 v230, v96, v97
	v_cvt_pk_bf16_f32 v231, v98, v99
	s_nop 1
	v_permlane32_swap_b32_e32 v228, v230
	v_permlane32_swap_b32_e32 v229, v231
	s_nop 0
	global_store_dwordx4 v219, v[228:231], s[8:9] offset:96
	v_cvt_pk_bf16_f32 v224, v36, v37
	v_cvt_pk_bf16_f32 v225, v38, v39
	v_cvt_pk_bf16_f32 v226, v40, v41
	v_cvt_pk_bf16_f32 v227, v42, v43
	s_nop 1
	v_permlane32_swap_b32_e32 v224, v226
	v_permlane32_swap_b32_e32 v225, v227
	s_nop 0
	global_store_dwordx4 v218, v[224:227], s[8:9] offset:256
	v_cvt_pk_bf16_f32 v228, v44, v45
	v_cvt_pk_bf16_f32 v229, v46, v47
	v_cvt_pk_bf16_f32 v230, v48, v49
	v_cvt_pk_bf16_f32 v231, v50, v51
	s_nop 1
	v_permlane32_swap_b32_e32 v228, v230
	v_permlane32_swap_b32_e32 v229, v231
	s_nop 0
	global_store_dwordx4 v218, v[228:231], s[8:9] offset:288
	v_cvt_pk_bf16_f32 v224, v100, v101
	v_cvt_pk_bf16_f32 v225, v102, v103
	v_cvt_pk_bf16_f32 v226, v104, v105
	v_cvt_pk_bf16_f32 v227, v106, v107
	s_nop 1
	v_permlane32_swap_b32_e32 v224, v226
	v_permlane32_swap_b32_e32 v225, v227
	s_nop 0
	global_store_dwordx4 v219, v[224:227], s[8:9] offset:256
	v_cvt_pk_bf16_f32 v228, v108, v109
	v_cvt_pk_bf16_f32 v229, v110, v111
	v_cvt_pk_bf16_f32 v230, v112, v113
	v_cvt_pk_bf16_f32 v231, v114, v115
	s_nop 1
	v_permlane32_swap_b32_e32 v228, v230
	v_permlane32_swap_b32_e32 v229, v231
	s_nop 0
	global_store_dwordx4 v219, v[228:231], s[8:9] offset:288
	v_cvt_pk_bf16_f32 v224, v52, v53
	v_cvt_pk_bf16_f32 v225, v54, v55
	v_cvt_pk_bf16_f32 v226, v56, v57
	v_cvt_pk_bf16_f32 v227, v58, v59
	s_nop 1
	v_permlane32_swap_b32_e32 v224, v226
	v_permlane32_swap_b32_e32 v225, v227
	s_nop 0
	global_store_dwordx4 v218, v[224:227], s[8:9] offset:320
	v_cvt_pk_bf16_f32 v228, v60, v61
	v_cvt_pk_bf16_f32 v229, v62, v63
	v_cvt_pk_bf16_f32 v230, v64, v65
	v_cvt_pk_bf16_f32 v231, v66, v67
	s_nop 1
	v_permlane32_swap_b32_e32 v228, v230
	v_permlane32_swap_b32_e32 v229, v231
	s_nop 0
	global_store_dwordx4 v218, v[228:231], s[8:9] offset:352
	v_cvt_pk_bf16_f32 v224, v116, v117
	v_cvt_pk_bf16_f32 v225, v118, v119
	v_cvt_pk_bf16_f32 v226, v120, v121
	v_cvt_pk_bf16_f32 v227, v122, v123
	s_nop 1
	v_permlane32_swap_b32_e32 v224, v226
	v_permlane32_swap_b32_e32 v225, v227
	s_nop 0
	global_store_dwordx4 v219, v[224:227], s[8:9] offset:320
	v_cvt_pk_bf16_f32 v228, v124, v125
	v_cvt_pk_bf16_f32 v229, v126, v127
	v_cvt_pk_bf16_f32 v230, v128, v129
	v_cvt_pk_bf16_f32 v231, v130, v131
	s_nop 1
	v_permlane32_swap_b32_e32 v228, v230
	v_permlane32_swap_b32_e32 v229, v231
	s_nop 0
	global_store_dwordx4 v219, v[228:231], s[8:9] offset:352
